# mlp1->LN2 grid barrier also replaced by per-tile completion records (32 per row block); LN2 polls its row block, reads U/X with sc1 loads
# speedup vs baseline: 1.0213x; 1.0012x over previous
.LBB0_8:
	s_cmp_le_i32 s18, s80
	s_cbranch_scc1 .LBB0_74
	s_cmp_eq_u32 s18, 5
	s_cbranch_scc1 .LBB0_74
	s_cmp_eq_u32 s18, 6
	s_cbranch_scc1 .LBB0_74
	s_cmp_eq_u32 s18, 11
	s_cbranch_scc1 .LBB0_74
	s_cmp_eq_u32 s18, 16
	s_cbranch_scc1 .LBB0_74
	s_cmp_eq_u32 s18, 21
	s_cbranch_scc1 .LBB0_74
	s_cmp_eq_u32 s18, 10
	s_cbranch_scc1 .LBB0_74
	s_cmp_eq_u32 s18, 15
	s_cbranch_scc1 .LBB0_74
	s_cmp_eq_u32 s18, 20
	s_cbranch_scc1 .LBB0_74
	v_readlane_b32 s0, v253, 19
	v_readlane_b32 s1, v253, 20
	s_andn2_b64 vcc, exec, s[0:1]
	s_cbranch_vccnz .LBB0_21
	s_barrier
	s_mov_b64 s[0:1], exec
	v_readlane_b32 s8, v253, 21
	v_readlane_b32 s9, v253, 22
	s_and_b64 s[8:9], s[0:1], s[8:9]
	s_mov_b64 exec, s[8:9]
	s_cbranch_execz .LBB0_20
	buffer_wbl2 sc1
	s_waitcnt vmcnt(0)
	s_load_dwordx2 s[22:23], s[78:79], 0x58
	s_mov_b64 s[26:27], exec
	v_mbcnt_lo_u32_b32 v2, s26, 0
	v_mbcnt_hi_u32_b32 v2, s27, v2
	v_cmp_eq_u32_e32 vcc, 0, v2
	s_waitcnt lgkmcnt(0)
	global_load_dword v0, v1, s[22:23] offset:40
	s_and_saveexec_b64 s[34:35], vcc
	s_cbranch_execz .LBB0_13
	s_bcnt1_i32_b64 s5, s[26:27]
	v_mov_b32_e32 v3, s5
	global_atomic_add v3, v1, v3, s[22:23] offset:32 sc0

.LBB0_74:
	s_add_i32 s0, s18, -2
	s_mul_hi_u32 s1, s0, 0xcccccccd
	s_lshr_b32 s1, s1, 2
	s_mul_i32 s5, s1, 5
	s_sub_i32 s5, s0, s5
	s_cmp_lt_i32 s18, 2
	s_cselect_b32 s8, 0, s1
	s_mov_b32 s9, s21
	s_cselect_b32 s6, s0, s5
	s_lshl_b64 s[0:1], s[8:9], 23
	v_writelane_b32 v255, s0, 35
	s_lshl_b32 s5, s8, 10
	s_nop 0
	v_writelane_b32 v255, s1, 36
	s_mul_i32 s0, s8, 3
	v_writelane_b32 v255, s0, 37
	s_mul_i32 s0, s8, 0x60
	v_writelane_b32 v255, s0, 38
	s_nop 1
	v_writelane_b32 v255, s1, 39
	v_writelane_b32 v255, s8, 40
	s_cmp_lt_u32 s8, 3
	s_cselect_b64 s[0:1], -1, 0
	v_writelane_b32 v255, s9, 41
	v_readlane_b32 s8, v254, 37
	v_readlane_b32 s9, v254, 38
	s_and_b64 s[0:1], s[8:9], s[0:1]
	v_writelane_b32 v255, s0, 42
	s_mov_b64 s[8:9], 0
	s_cmp_lt_i32 s6, 1
	v_writelane_b32 v255, s1, 43
	v_writelane_b32 v255, s6, 44
	v_writelane_b32 v255, s8, 45
	s_mov_b64 s[0:1], -1
	s_nop 0
	v_writelane_b32 v255, s9, 46
	s_cbranch_scc1 .LBB0_339
	v_readlane_b32 s0, v255, 44
	s_cmp_gt_i32 s0, 1
	s_cbranch_scc0 .LBB0_87
	s_cmp_gt_i32 s0, 2
	s_cbranch_scc0 .LBB0_88
	s_cmp_eq_u32 s0, 3
	s_mov_b64 s[0:1], -1
	s_cbranch_scc0 .LBB0_90
	s_mov_b64 s[22:23], 0
	s_mov_b64 s[0:1], 0
	v_mov_b32_e32 v0, v137
	v_readlane_b32 s8, v254, 33
	v_readlane_b32 s9, v254, 34
	v_readfirstlane_b32 s0, v0
	s_ashr_i32 s0, s0, 6
	s_andn2_b64 vcc, exec, s[8:9]
	s_cbranch_vccnz .LBB0_89
	s_and_b32 s1, s0, 1
	s_ashr_i32 s6, s0, 1
	s_add_u32 s12, s94, s22
	s_addc_u32 s13, s95, s23
	v_readlane_b32 s16, v255, 35
	v_readlane_b32 s17, v255, 36
	s_add_u32 s8, s12, s16
	s_addc_u32 s9, s13, s17
	s_add_u32 s26, s8, 0x2300000
	s_addc_u32 s27, s9, 0
	s_add_u32 s34, s12, 0x7b48000
	v_bfe_u32 v8, v0, 3, 3
	s_addc_u32 s35, s13, 0
	v_lshl_or_b32 v98, s0, 5, v8
	s_lshl_b32 s8, s0, 12
	s_lshl_b32 s9, s0, 11
	s_lshl_b32 s11, s6, 13
	s_lshl_b32 s6, s6, 6
	s_lshl_b32 s14, s1, 13
	s_lshl_b32 s19, s1, 6
	v_bfe_u32 v3, v0, 4, 2
	v_ashrrev_i32_e32 v99, 31, v98
	v_lshl_or_b32 v104, s0, 4, v8
	s_add_u32 s0, s12, 0xe1d8000
	v_and_b32_e32 v2, 15, v0
	v_lshlrev_b64 v[4:5], 11, v[98:99]
	v_and_b32_e32 v10, 7, v0
	v_bitop3_b32 v9, v8, v0, 7 bitop3:0x78
	v_bitop3_b32 v0, v3, v0, 7 bitop3:0x78
	s_addc_u32 s1, s13, 0
	v_lshl_add_u64 v[6:7], s[34:35], 0, v[4:5]
	v_lshlrev_b32_e32 v100, 4, v9
	v_mov_b32_e32 v101, v1
	v_ashrrev_i32_e32 v105, 31, v104
	v_lshlrev_b32_e32 v120, 4, v0
	v_or_b32_e32 v0, s6, v2
	v_lshl_or_b32 v125, v3, 2, s6
	s_add_u32 s6, s22, s16
	v_lshl_add_u64 v[102:103], v[6:7], 0, v[100:101]
	v_lshlrev_b64 v[6:7], 11, v[104:105]
	v_lshlrev_b32_e32 v99, 7, v2
	v_or_b32_e32 v11, s19, v2
	v_bitop3_b32 v10, v3, v10, 4 bitop3:0x36
	v_lshl_add_u64 v[112:113], s[12:13], 0, v[4:5]
	s_addc_u32 s13, s23, s17
	v_lshl_add_u64 v[8:9], s[26:27], 0, v[6:7]
	v_or_b32_e32 v105, s11, v99
	v_lshlrev_b32_e32 v121, 7, v0
	v_or_b32_e32 v122, s14, v99
	v_lshlrev_b32_e32 v123, 7, v11
	v_lshlrev_b32_e32 v124, 4, v10
	s_add_u32 s12, s94, s6
	v_lshl_add_u64 v[106:107], v[8:9], 0, v[100:101]
	v_or_b32_e32 v0, 0x800, v121
	v_or_b32_e32 v8, 0x1000, v121
	v_or_b32_e32 v9, 0x1800, v121
	v_or_b32_e32 v11, 0x800, v123
	v_or_b32_e32 v12, 0x1000, v123
	v_or_b32_e32 v13, 0x1800, v123
	v_or_b32_e32 v3, 0x18000, v124
	v_or_b32_e32 v10, 0x20000, v122
	s_waitcnt vmcnt(0)
	v_or_b32_e32 v14, 0x20000, v124
	v_add_u32_e32 v15, 0xc000, v105
	v_add_u32_e32 v16, 0xc000, v121
	v_or_b32_e32 v17, 0xc000, v122
	v_or_b32_e32 v18, 0xc000, v123
	s_addc_u32 s13, s95, s13
	v_or_b32_e32 v127, s11, v124
	v_or_b32_e32 v4, s14, v120
	s_add_i32 s11, s11, 0xc000
	v_add_u32_e32 v135, v122, v120
	v_lshl_add_u64 v[108:109], s[34:35], 0, v[100:101]
	v_lshl_add_u64 v[110:111], s[26:27], 0, v[100:101]
	v_add_u32_e32 v126, 0x18000, v105
	v_lshl_add_u64 v[114:115], s[12:13], 0, v[6:7]
	v_or_b32_e32 v128, 0x15000, v4
	v_or_b32_e32 v129, 0x14800, v4
	v_or_b32_e32 v130, 0x14000, v4
	v_or_b32_e32 v131, s14, v124
	v_or_b32_e32 v132, s11, v120
	s_mov_b64 s[38:39], 0
	s_add_i32 s11, s8, 0x400
	s_add_i32 s12, s8, 0xc00
	s_add_i32 s13, s9, 0x8000
	s_add_i32 s40, s9, 0x8400
	s_add_i32 s41, s8, 0xc400
	s_add_i32 s42, s8, 0xc800
	s_add_i32 s43, s8, 0xcc00
	s_add_i32 s44, s9, 0x14400
	s_add_i32 s45, s8, 0x18400
	s_add_i32 s46, s8, 0x18800
	s_add_i32 s47, s8, 0x18c00
	s_add_i32 s48, s9, 0x20400
	v_add_u32_e32 v133, v105, v120
	v_add_u32_e32 v134, v121, v120
	v_add_u32_e32 v161, v123, v120
	v_add_u32_e32 v163, v15, v124
	v_add_u32_e32 v164, v16, v124
	v_add_u32_e32 v165, v17, v124
	v_add_u32_e32 v166, v18, v124
	v_add3_u32 v167, v121, v120, s29
	v_or_b32_e32 v168, 0x20000, v135
	v_add_u32_e32 v169, v3, v0
	v_add_u32_e32 v170, v3, v8
	v_add_u32_e32 v171, v3, v9
	v_add_u32_e32 v172, v10, v124
	v_add_u32_e32 v173, v14, v11
	v_add_u32_e32 v174, v14, v12
	v_add_u32_e32 v175, v14, v13
	s_lshl_b32 s20, s19, 1
	v_lshlrev_b32_e32 v0, 1, v2
	v_readlane_b32 s49, v253, 0
	s_mov_b32 s66, 0
	s_branch .LBB0_81
.LBB0_80:
	s_lshl_b32 s66, s26, 1
	s_lshr_b32 s67, s22, 3
	s_add_i32 s66, s66, s67
	s_add_i32 s66, s66, 1
	v_readfirstlane_b32 s6, v137
	s_lshr_b32 s6, s6, 6
	s_and_b32 s14, s6, 1
	s_lshr_b32 s19, s6, 1
	s_lshl_b32 s19, s19, 6
	s_add_i32 s19, s19, s26
	s_lshl_b32 s14, s14, 6
	s_add_i32 s14, s14, s22
	s_lshl_b32 s6, s6, 12
	s_add_i32 s6, s6, 0x18000
	v_and_b32_e32 v202, 63, v137
	v_and_b32_e32 v203, 15, v202
	v_lshrrev_b32_e32 v204, 4, v202
	v_and_b32_e32 v205, 3, v203
	v_lshrrev_b32_e32 v206, 2, v203
	v_lshl_or_b32 v207, v204, 2, v205
	s_mov_b32 s36, 0xaaaaaaaa
	s_mov_b32 s37, 0xaaaaaaaa
	s_mov_b32 s50, 0xcccccccc
	s_mov_b32 s51, 0xcccccccc
	v_and_b32_e32 v208, 7, v207
	v_lshlrev_b32_e32 v208, 1, v208
	v_or_b32_e32 v209, 0, v206
	v_xor_b32_e32 v209, v209, v208
	v_lshlrev_b32_e32 v209, 3, v209
	v_lshl_add_u32 v209, v207, 7, v209
	v_add_u32_e32 v209, s6, v209
	v_or_b32_e32 v210, 4, v206
	v_xor_b32_e32 v210, v210, v208
	v_lshlrev_b32_e32 v210, 3, v210
	v_lshl_add_u32 v210, v207, 7, v210
	v_add_u32_e32 v210, s6, v210
	v_or_b32_e32 v211, 8, v206
	v_xor_b32_e32 v211, v211, v208
	v_lshlrev_b32_e32 v211, 3, v211
	v_lshl_add_u32 v211, v207, 7, v211
	v_add_u32_e32 v211, s6, v211
	v_or_b32_e32 v212, 12, v206
	v_xor_b32_e32 v212, v212, v208
	v_lshlrev_b32_e32 v212, 3, v212
	v_lshl_add_u32 v212, v207, 7, v212
	v_add_u32_e32 v212, s6, v212
	v_lshl_add_u32 v213, v202, 4, s6
	v_lshrrev_b32_e32 v214, 3, v202
	v_and_b32_e32 v215, 7, v202
	v_xor_b32_e32 v215, v215, v214
	v_add_u32_e32 v214, s19, v214
	v_lshlrev_b32_e32 v214, 13, v214
	v_lshl_add_u32 v214, v215, 4, v214
	s_lshl_b32 s27, s14, 1
	v_add_u32_e32 v214, s27, v214
	s_add_u32 s16, s94, 0xe1d8000
	s_addc_u32 s17, s95, 0
	v_max_f32_e32 v62, 0, v62
	v_max_f32_e32 v63, 0, v63
	v_max_f32_e32 v64, 0, v64
	v_max_f32_e32 v65, 0, v65
	v_mul_f32_e32 v62, v62, v62
	v_mul_f32_e32 v63, v63, v63
	v_mul_f32_e32 v64, v64, v64
	v_mul_f32_e32 v65, v65, v65
	v_max_f32_e32 v58, 0, v58
	v_max_f32_e32 v59, 0, v59
	v_max_f32_e32 v60, 0, v60
	v_max_f32_e32 v61, 0, v61
	v_mul_f32_e32 v58, v58, v58
	v_mul_f32_e32 v59, v59, v59
	v_mul_f32_e32 v60, v60, v60
	v_mul_f32_e32 v61, v61, v61
	v_max_f32_e32 v54, 0, v54
	v_max_f32_e32 v55, 0, v55
	v_max_f32_e32 v56, 0, v56
	v_max_f32_e32 v57, 0, v57
	v_mul_f32_e32 v54, v54, v54
	v_mul_f32_e32 v55, v55, v55
	v_mul_f32_e32 v56, v56, v56
	v_mul_f32_e32 v57, v57, v57
	v_max_f32_e32 v50, 0, v50
	v_max_f32_e32 v51, 0, v51
	v_max_f32_e32 v52, 0, v52
	v_max_f32_e32 v53, 0, v53
	v_mul_f32_e32 v50, v50, v50
	v_mul_f32_e32 v51, v51, v51
	v_mul_f32_e32 v52, v52, v52
	v_mul_f32_e32 v53, v53, v53
	v_max_f32_e32 v46, 0, v46
	v_max_f32_e32 v47, 0, v47
	v_max_f32_e32 v48, 0, v48
	v_max_f32_e32 v49, 0, v49
	v_mul_f32_e32 v46, v46, v46
	v_mul_f32_e32 v47, v47, v47
	v_mul_f32_e32 v48, v48, v48
	v_mul_f32_e32 v49, v49, v49
	v_max_f32_e32 v42, 0, v42
	v_max_f32_e32 v43, 0, v43
	v_max_f32_e32 v44, 0, v44
	v_max_f32_e32 v45, 0, v45
	v_mul_f32_e32 v42, v42, v42
	v_mul_f32_e32 v43, v43, v43
	v_mul_f32_e32 v44, v44, v44
	v_mul_f32_e32 v45, v45, v45
	v_max_f32_e32 v38, 0, v38
	v_max_f32_e32 v39, 0, v39
	v_max_f32_e32 v40, 0, v40
	v_max_f32_e32 v41, 0, v41
	v_mul_f32_e32 v38, v38, v38
	v_mul_f32_e32 v39, v39, v39
	v_mul_f32_e32 v40, v40, v40
	v_mul_f32_e32 v41, v41, v41
	v_max_f32_e32 v34, 0, v34
	v_max_f32_e32 v35, 0, v35
	v_max_f32_e32 v36, 0, v36
	v_max_f32_e32 v37, 0, v37
	v_mul_f32_e32 v34, v34, v34
	v_mul_f32_e32 v35, v35, v35
	v_mul_f32_e32 v36, v36, v36
	v_mul_f32_e32 v37, v37, v37
	s_nop 1
	v_mov_b32_dpp v72, v63 quad_perm:[1,0,3,2] row_mask:0xf bank_mask:0xf
	v_mov_b32_dpp v73, v62 quad_perm:[1,0,3,2] row_mask:0xf bank_mask:0xf
	v_mov_b32_dpp v74, v65 quad_perm:[1,0,3,2] row_mask:0xf bank_mask:0xf
	v_mov_b32_dpp v75, v64 quad_perm:[1,0,3,2] row_mask:0xf bank_mask:0xf
	v_cndmask_b32_e64 v62, v62, v72, s[36:37]
	v_cndmask_b32_e64 v63, v73, v63, s[36:37]
	v_cndmask_b32_e64 v64, v64, v74, s[36:37]
	v_cndmask_b32_e64 v65, v75, v65, s[36:37]
	s_nop 1
	v_mov_b32_dpp v74, v62 quad_perm:[2,3,0,1] row_mask:0xf bank_mask:0xf
	v_mov_b32_dpp v75, v63 quad_perm:[2,3,0,1] row_mask:0xf bank_mask:0xf
	v_mov_b32_dpp v72, v64 quad_perm:[2,3,0,1] row_mask:0xf bank_mask:0xf
	v_mov_b32_dpp v73, v65 quad_perm:[2,3,0,1] row_mask:0xf bank_mask:0xf
	v_cndmask_b32_e64 v62, v62, v72, s[50:51]
	v_cndmask_b32_e64 v63, v63, v73, s[50:51]
	v_cndmask_b32_e64 v64, v74, v64, s[50:51]
	v_cndmask_b32_e64 v65, v75, v65, s[50:51]
	s_nop 1
	v_mov_b32_dpp v72, v59 quad_perm:[1,0,3,2] row_mask:0xf bank_mask:0xf
	v_mov_b32_dpp v73, v58 quad_perm:[1,0,3,2] row_mask:0xf bank_mask:0xf
	v_mov_b32_dpp v74, v61 quad_perm:[1,0,3,2] row_mask:0xf bank_mask:0xf
	v_mov_b32_dpp v75, v60 quad_perm:[1,0,3,2] row_mask:0xf bank_mask:0xf
	v_cndmask_b32_e64 v58, v58, v72, s[36:37]
	v_cndmask_b32_e64 v59, v73, v59, s[36:37]
	v_cndmask_b32_e64 v60, v60, v74, s[36:37]
	v_cndmask_b32_e64 v61, v75, v61, s[36:37]
	s_nop 1
	v_mov_b32_dpp v74, v58 quad_perm:[2,3,0,1] row_mask:0xf bank_mask:0xf
	v_mov_b32_dpp v75, v59 quad_perm:[2,3,0,1] row_mask:0xf bank_mask:0xf
	v_mov_b32_dpp v72, v60 quad_perm:[2,3,0,1] row_mask:0xf bank_mask:0xf
	v_mov_b32_dpp v73, v61 quad_perm:[2,3,0,1] row_mask:0xf bank_mask:0xf
	v_cndmask_b32_e64 v58, v58, v72, s[50:51]
	v_cndmask_b32_e64 v59, v59, v73, s[50:51]
	v_cndmask_b32_e64 v60, v74, v60, s[50:51]
	v_cndmask_b32_e64 v61, v75, v61, s[50:51]
	s_nop 1
	v_mov_b32_dpp v72, v55 quad_perm:[1,0,3,2] row_mask:0xf bank_mask:0xf
	v_mov_b32_dpp v73, v54 quad_perm:[1,0,3,2] row_mask:0xf bank_mask:0xf
	v_mov_b32_dpp v74, v57 quad_perm:[1,0,3,2] row_mask:0xf bank_mask:0xf
	v_mov_b32_dpp v75, v56 quad_perm:[1,0,3,2] row_mask:0xf bank_mask:0xf
	v_cndmask_b32_e64 v54, v54, v72, s[36:37]
	v_cndmask_b32_e64 v55, v73, v55, s[36:37]
	v_cndmask_b32_e64 v56, v56, v74, s[36:37]
	v_cndmask_b32_e64 v57, v75, v57, s[36:37]
	s_nop 1
	v_mov_b32_dpp v74, v54 quad_perm:[2,3,0,1] row_mask:0xf bank_mask:0xf
	v_mov_b32_dpp v75, v55 quad_perm:[2,3,0,1] row_mask:0xf bank_mask:0xf
	v_mov_b32_dpp v72, v56 quad_perm:[2,3,0,1] row_mask:0xf bank_mask:0xf
	v_mov_b32_dpp v73, v57 quad_perm:[2,3,0,1] row_mask:0xf bank_mask:0xf
	v_cndmask_b32_e64 v54, v54, v72, s[50:51]
	v_cndmask_b32_e64 v55, v55, v73, s[50:51]
	v_cndmask_b32_e64 v56, v74, v56, s[50:51]
	v_cndmask_b32_e64 v57, v75, v57, s[50:51]
	s_nop 1
	v_mov_b32_dpp v72, v51 quad_perm:[1,0,3,2] row_mask:0xf bank_mask:0xf
	v_mov_b32_dpp v73, v50 quad_perm:[1,0,3,2] row_mask:0xf bank_mask:0xf
	v_mov_b32_dpp v74, v53 quad_perm:[1,0,3,2] row_mask:0xf bank_mask:0xf
	v_mov_b32_dpp v75, v52 quad_perm:[1,0,3,2] row_mask:0xf bank_mask:0xf
	v_cndmask_b32_e64 v50, v50, v72, s[36:37]
	v_cndmask_b32_e64 v51, v73, v51, s[36:37]
	v_cndmask_b32_e64 v52, v52, v74, s[36:37]
	v_cndmask_b32_e64 v53, v75, v53, s[36:37]
	s_nop 1
	v_mov_b32_dpp v74, v50 quad_perm:[2,3,0,1] row_mask:0xf bank_mask:0xf
	v_mov_b32_dpp v75, v51 quad_perm:[2,3,0,1] row_mask:0xf bank_mask:0xf
	v_mov_b32_dpp v72, v52 quad_perm:[2,3,0,1] row_mask:0xf bank_mask:0xf
	v_mov_b32_dpp v73, v53 quad_perm:[2,3,0,1] row_mask:0xf bank_mask:0xf
	v_cndmask_b32_e64 v50, v50, v72, s[50:51]
	v_cndmask_b32_e64 v51, v51, v73, s[50:51]
	v_cndmask_b32_e64 v52, v74, v52, s[50:51]
	v_cndmask_b32_e64 v53, v75, v53, s[50:51]
	s_nop 1
	v_mov_b32_dpp v72, v47 quad_perm:[1,0,3,2] row_mask:0xf bank_mask:0xf
	v_mov_b32_dpp v73, v46 quad_perm:[1,0,3,2] row_mask:0xf bank_mask:0xf
	v_mov_b32_dpp v74, v49 quad_perm:[1,0,3,2] row_mask:0xf bank_mask:0xf
	v_mov_b32_dpp v75, v48 quad_perm:[1,0,3,2] row_mask:0xf bank_mask:0xf
	v_cndmask_b32_e64 v46, v46, v72, s[36:37]
	v_cndmask_b32_e64 v47, v73, v47, s[36:37]
	v_cndmask_b32_e64 v48, v48, v74, s[36:37]
	v_cndmask_b32_e64 v49, v75, v49, s[36:37]
	s_nop 1
	v_mov_b32_dpp v74, v46 quad_perm:[2,3,0,1] row_mask:0xf bank_mask:0xf
	v_mov_b32_dpp v75, v47 quad_perm:[2,3,0,1] row_mask:0xf bank_mask:0xf
	v_mov_b32_dpp v72, v48 quad_perm:[2,3,0,1] row_mask:0xf bank_mask:0xf
	v_mov_b32_dpp v73, v49 quad_perm:[2,3,0,1] row_mask:0xf bank_mask:0xf
	v_cndmask_b32_e64 v46, v46, v72, s[50:51]
	v_cndmask_b32_e64 v47, v47, v73, s[50:51]
	v_cndmask_b32_e64 v48, v74, v48, s[50:51]
	v_cndmask_b32_e64 v49, v75, v49, s[50:51]
	s_nop 1
	v_mov_b32_dpp v72, v43 quad_perm:[1,0,3,2] row_mask:0xf bank_mask:0xf
	v_mov_b32_dpp v73, v42 quad_perm:[1,0,3,2] row_mask:0xf bank_mask:0xf
	v_mov_b32_dpp v74, v45 quad_perm:[1,0,3,2] row_mask:0xf bank_mask:0xf
	v_mov_b32_dpp v75, v44 quad_perm:[1,0,3,2] row_mask:0xf bank_mask:0xf
	v_cndmask_b32_e64 v42, v42, v72, s[36:37]
	v_cndmask_b32_e64 v43, v73, v43, s[36:37]
	v_cndmask_b32_e64 v44, v44, v74, s[36:37]
	v_cndmask_b32_e64 v45, v75, v45, s[36:37]
	s_nop 1
	v_mov_b32_dpp v74, v42 quad_perm:[2,3,0,1] row_mask:0xf bank_mask:0xf
	v_mov_b32_dpp v75, v43 quad_perm:[2,3,0,1] row_mask:0xf bank_mask:0xf
	v_mov_b32_dpp v72, v44 quad_perm:[2,3,0,1] row_mask:0xf bank_mask:0xf
	v_mov_b32_dpp v73, v45 quad_perm:[2,3,0,1] row_mask:0xf bank_mask:0xf
	v_cndmask_b32_e64 v42, v42, v72, s[50:51]
	v_cndmask_b32_e64 v43, v43, v73, s[50:51]
	v_cndmask_b32_e64 v44, v74, v44, s[50:51]
	v_cndmask_b32_e64 v45, v75, v45, s[50:51]
	s_nop 1
	v_mov_b32_dpp v72, v39 quad_perm:[1,0,3,2] row_mask:0xf bank_mask:0xf
	v_mov_b32_dpp v73, v38 quad_perm:[1,0,3,2] row_mask:0xf bank_mask:0xf
	v_mov_b32_dpp v74, v41 quad_perm:[1,0,3,2] row_mask:0xf bank_mask:0xf
	v_mov_b32_dpp v75, v40 quad_perm:[1,0,3,2] row_mask:0xf bank_mask:0xf
	v_cndmask_b32_e64 v38, v38, v72, s[36:37]
	v_cndmask_b32_e64 v39, v73, v39, s[36:37]
	v_cndmask_b32_e64 v40, v40, v74, s[36:37]
	v_cndmask_b32_e64 v41, v75, v41, s[36:37]
	s_nop 1
	v_mov_b32_dpp v74, v38 quad_perm:[2,3,0,1] row_mask:0xf bank_mask:0xf
	v_mov_b32_dpp v75, v39 quad_perm:[2,3,0,1] row_mask:0xf bank_mask:0xf
	v_mov_b32_dpp v72, v40 quad_perm:[2,3,0,1] row_mask:0xf bank_mask:0xf
	v_mov_b32_dpp v73, v41 quad_perm:[2,3,0,1] row_mask:0xf bank_mask:0xf
	v_cndmask_b32_e64 v38, v38, v72, s[50:51]
	v_cndmask_b32_e64 v39, v39, v73, s[50:51]
	v_cndmask_b32_e64 v40, v74, v40, s[50:51]
	v_cndmask_b32_e64 v41, v75, v41, s[50:51]
	s_nop 1
	v_mov_b32_dpp v72, v35 quad_perm:[1,0,3,2] row_mask:0xf bank_mask:0xf
	v_mov_b32_dpp v73, v34 quad_perm:[1,0,3,2] row_mask:0xf bank_mask:0xf
	v_mov_b32_dpp v74, v37 quad_perm:[1,0,3,2] row_mask:0xf bank_mask:0xf
	v_mov_b32_dpp v75, v36 quad_perm:[1,0,3,2] row_mask:0xf bank_mask:0xf
	v_cndmask_b32_e64 v34, v34, v72, s[36:37]
	v_cndmask_b32_e64 v35, v73, v35, s[36:37]
	v_cndmask_b32_e64 v36, v36, v74, s[36:37]
	v_cndmask_b32_e64 v37, v75, v37, s[36:37]
	s_nop 1
	v_mov_b32_dpp v74, v34 quad_perm:[2,3,0,1] row_mask:0xf bank_mask:0xf
	v_mov_b32_dpp v75, v35 quad_perm:[2,3,0,1] row_mask:0xf bank_mask:0xf
	v_mov_b32_dpp v72, v36 quad_perm:[2,3,0,1] row_mask:0xf bank_mask:0xf
	v_mov_b32_dpp v73, v37 quad_perm:[2,3,0,1] row_mask:0xf bank_mask:0xf
	v_cndmask_b32_e64 v34, v34, v72, s[50:51]
	v_cndmask_b32_e64 v35, v35, v73, s[50:51]
	v_cndmask_b32_e64 v36, v74, v36, s[50:51]
	v_cndmask_b32_e64 v37, v75, v37, s[50:51]
	v_cvt_pk_bf16_f32 v62, v62, v63
	v_cvt_pk_bf16_f32 v63, v64, v65
	ds_write_b64 v209, v[62:63] offset:0
	v_cvt_pk_bf16_f32 v58, v58, v59
	v_cvt_pk_bf16_f32 v59, v60, v61
	ds_write_b64 v210, v[58:59] offset:0
	v_cvt_pk_bf16_f32 v54, v54, v55
	v_cvt_pk_bf16_f32 v55, v56, v57
	ds_write_b64 v211, v[54:55] offset:0
	v_cvt_pk_bf16_f32 v50, v50, v51
	v_cvt_pk_bf16_f32 v51, v52, v53
	ds_write_b64 v212, v[50:51] offset:0
	v_cvt_pk_bf16_f32 v46, v46, v47
	v_cvt_pk_bf16_f32 v47, v48, v49
	ds_write_b64 v209, v[46:47] offset:2048
	v_cvt_pk_bf16_f32 v42, v42, v43
	v_cvt_pk_bf16_f32 v43, v44, v45
	ds_write_b64 v210, v[42:43] offset:2048
	v_cvt_pk_bf16_f32 v38, v38, v39
	v_cvt_pk_bf16_f32 v39, v40, v41
	ds_write_b64 v211, v[38:39] offset:2048
	v_cvt_pk_bf16_f32 v34, v34, v35
	v_cvt_pk_bf16_f32 v35, v36, v37
	ds_write_b64 v212, v[34:35] offset:2048
	s_waitcnt lgkmcnt(0)
	ds_read_b128 v[76:79], v213 offset:0
	ds_read_b128 v[80:83], v213 offset:1024
	ds_read_b128 v[84:87], v213 offset:2048
	ds_read_b128 v[88:91], v213 offset:3072
	s_waitcnt lgkmcnt(3)
	global_store_dwordx4 v214, v[76:79], s[16:17] sc1
	s_waitcnt lgkmcnt(2)
	v_add_u32_e32 v216, 0x10000, v214
	global_store_dwordx4 v216, v[80:83], s[16:17] sc1
	s_waitcnt lgkmcnt(1)
	v_add_u32_e32 v216, 0x20000, v214
	global_store_dwordx4 v216, v[84:87], s[16:17] sc1
	s_waitcnt lgkmcnt(0)
	v_add_u32_e32 v216, 0x30000, v214
	global_store_dwordx4 v216, v[88:91], s[16:17] sc1
	s_nop 1
	v_max_f32_e32 v30, 0, v30
	v_max_f32_e32 v31, 0, v31
	v_max_f32_e32 v32, 0, v32
	v_max_f32_e32 v33, 0, v33
	v_mul_f32_e32 v30, v30, v30
	v_mul_f32_e32 v31, v31, v31
	v_mul_f32_e32 v32, v32, v32
	v_mul_f32_e32 v33, v33, v33
	v_max_f32_e32 v26, 0, v26
	v_max_f32_e32 v27, 0, v27
	v_max_f32_e32 v28, 0, v28
	v_max_f32_e32 v29, 0, v29
	v_mul_f32_e32 v26, v26, v26
	v_mul_f32_e32 v27, v27, v27
	v_mul_f32_e32 v28, v28, v28
	v_mul_f32_e32 v29, v29, v29
	v_max_f32_e32 v22, 0, v22
	v_max_f32_e32 v23, 0, v23
	v_max_f32_e32 v24, 0, v24
	v_max_f32_e32 v25, 0, v25
	v_mul_f32_e32 v22, v22, v22
	v_mul_f32_e32 v23, v23, v23
	v_mul_f32_e32 v24, v24, v24
	v_mul_f32_e32 v25, v25, v25
	v_max_f32_e32 v18, 0, v18
	v_max_f32_e32 v19, 0, v19
	v_max_f32_e32 v20, 0, v20
	v_max_f32_e32 v21, 0, v21
	v_mul_f32_e32 v18, v18, v18
	v_mul_f32_e32 v19, v19, v19
	v_mul_f32_e32 v20, v20, v20
	v_mul_f32_e32 v21, v21, v21
	v_max_f32_e32 v14, 0, v14
	v_max_f32_e32 v15, 0, v15
	v_max_f32_e32 v16, 0, v16
	v_max_f32_e32 v17, 0, v17
	v_mul_f32_e32 v14, v14, v14
	v_mul_f32_e32 v15, v15, v15
	v_mul_f32_e32 v16, v16, v16
	v_mul_f32_e32 v17, v17, v17
	v_max_f32_e32 v10, 0, v10
	v_max_f32_e32 v11, 0, v11
	v_max_f32_e32 v12, 0, v12
	v_max_f32_e32 v13, 0, v13
	v_mul_f32_e32 v10, v10, v10
	v_mul_f32_e32 v11, v11, v11
	v_mul_f32_e32 v12, v12, v12
	v_mul_f32_e32 v13, v13, v13
	v_max_f32_e32 v6, 0, v6
	v_max_f32_e32 v7, 0, v7
	v_max_f32_e32 v8, 0, v8
	v_max_f32_e32 v9, 0, v9
	v_mul_f32_e32 v6, v6, v6
	v_mul_f32_e32 v7, v7, v7
	v_mul_f32_e32 v8, v8, v8
	v_mul_f32_e32 v9, v9, v9
	v_max_f32_e32 v2, 0, v2
	v_max_f32_e32 v3, 0, v3
	v_max_f32_e32 v4, 0, v4
	v_max_f32_e32 v5, 0, v5
	v_mul_f32_e32 v2, v2, v2
	v_mul_f32_e32 v3, v3, v3
	v_mul_f32_e32 v4, v4, v4
	v_mul_f32_e32 v5, v5, v5
	s_nop 1
	v_mov_b32_dpp v72, v31 quad_perm:[1,0,3,2] row_mask:0xf bank_mask:0xf
	v_mov_b32_dpp v73, v30 quad_perm:[1,0,3,2] row_mask:0xf bank_mask:0xf
	v_mov_b32_dpp v74, v33 quad_perm:[1,0,3,2] row_mask:0xf bank_mask:0xf
	v_mov_b32_dpp v75, v32 quad_perm:[1,0,3,2] row_mask:0xf bank_mask:0xf
	v_cndmask_b32_e64 v30, v30, v72, s[36:37]
	v_cndmask_b32_e64 v31, v73, v31, s[36:37]
	v_cndmask_b32_e64 v32, v32, v74, s[36:37]
	v_cndmask_b32_e64 v33, v75, v33, s[36:37]
	s_nop 1
	v_mov_b32_dpp v74, v30 quad_perm:[2,3,0,1] row_mask:0xf bank_mask:0xf
	v_mov_b32_dpp v75, v31 quad_perm:[2,3,0,1] row_mask:0xf bank_mask:0xf
	v_mov_b32_dpp v72, v32 quad_perm:[2,3,0,1] row_mask:0xf bank_mask:0xf
	v_mov_b32_dpp v73, v33 quad_perm:[2,3,0,1] row_mask:0xf bank_mask:0xf
	v_cndmask_b32_e64 v30, v30, v72, s[50:51]
	v_cndmask_b32_e64 v31, v31, v73, s[50:51]
	v_cndmask_b32_e64 v32, v74, v32, s[50:51]
	v_cndmask_b32_e64 v33, v75, v33, s[50:51]
	s_nop 1
	v_mov_b32_dpp v72, v27 quad_perm:[1,0,3,2] row_mask:0xf bank_mask:0xf
	v_mov_b32_dpp v73, v26 quad_perm:[1,0,3,2] row_mask:0xf bank_mask:0xf
	v_mov_b32_dpp v74, v29 quad_perm:[1,0,3,2] row_mask:0xf bank_mask:0xf
	v_mov_b32_dpp v75, v28 quad_perm:[1,0,3,2] row_mask:0xf bank_mask:0xf
	v_cndmask_b32_e64 v26, v26, v72, s[36:37]
	v_cndmask_b32_e64 v27, v73, v27, s[36:37]
	v_cndmask_b32_e64 v28, v28, v74, s[36:37]
	v_cndmask_b32_e64 v29, v75, v29, s[36:37]
	s_nop 1
	v_mov_b32_dpp v74, v26 quad_perm:[2,3,0,1] row_mask:0xf bank_mask:0xf
	v_mov_b32_dpp v75, v27 quad_perm:[2,3,0,1] row_mask:0xf bank_mask:0xf
	v_mov_b32_dpp v72, v28 quad_perm:[2,3,0,1] row_mask:0xf bank_mask:0xf
	v_mov_b32_dpp v73, v29 quad_perm:[2,3,0,1] row_mask:0xf bank_mask:0xf
	v_cndmask_b32_e64 v26, v26, v72, s[50:51]
	v_cndmask_b32_e64 v27, v27, v73, s[50:51]
	v_cndmask_b32_e64 v28, v74, v28, s[50:51]
	v_cndmask_b32_e64 v29, v75, v29, s[50:51]
	s_nop 1
	v_mov_b32_dpp v72, v23 quad_perm:[1,0,3,2] row_mask:0xf bank_mask:0xf
	v_mov_b32_dpp v73, v22 quad_perm:[1,0,3,2] row_mask:0xf bank_mask:0xf
	v_mov_b32_dpp v74, v25 quad_perm:[1,0,3,2] row_mask:0xf bank_mask:0xf
	v_mov_b32_dpp v75, v24 quad_perm:[1,0,3,2] row_mask:0xf bank_mask:0xf
	v_cndmask_b32_e64 v22, v22, v72, s[36:37]
	v_cndmask_b32_e64 v23, v73, v23, s[36:37]
	v_cndmask_b32_e64 v24, v24, v74, s[36:37]
	v_cndmask_b32_e64 v25, v75, v25, s[36:37]
	s_nop 1
	v_mov_b32_dpp v74, v22 quad_perm:[2,3,0,1] row_mask:0xf bank_mask:0xf
	v_mov_b32_dpp v75, v23 quad_perm:[2,3,0,1] row_mask:0xf bank_mask:0xf
	v_mov_b32_dpp v72, v24 quad_perm:[2,3,0,1] row_mask:0xf bank_mask:0xf
	v_mov_b32_dpp v73, v25 quad_perm:[2,3,0,1] row_mask:0xf bank_mask:0xf
	v_cndmask_b32_e64 v22, v22, v72, s[50:51]
	v_cndmask_b32_e64 v23, v23, v73, s[50:51]
	v_cndmask_b32_e64 v24, v74, v24, s[50:51]
	v_cndmask_b32_e64 v25, v75, v25, s[50:51]
	s_nop 1
	v_mov_b32_dpp v72, v19 quad_perm:[1,0,3,2] row_mask:0xf bank_mask:0xf
	v_mov_b32_dpp v73, v18 quad_perm:[1,0,3,2] row_mask:0xf bank_mask:0xf
	v_mov_b32_dpp v74, v21 quad_perm:[1,0,3,2] row_mask:0xf bank_mask:0xf
	v_mov_b32_dpp v75, v20 quad_perm:[1,0,3,2] row_mask:0xf bank_mask:0xf
	v_cndmask_b32_e64 v18, v18, v72, s[36:37]
	v_cndmask_b32_e64 v19, v73, v19, s[36:37]
	v_cndmask_b32_e64 v20, v20, v74, s[36:37]
	v_cndmask_b32_e64 v21, v75, v21, s[36:37]
	s_nop 1
	v_mov_b32_dpp v74, v18 quad_perm:[2,3,0,1] row_mask:0xf bank_mask:0xf
	v_mov_b32_dpp v75, v19 quad_perm:[2,3,0,1] row_mask:0xf bank_mask:0xf
	v_mov_b32_dpp v72, v20 quad_perm:[2,3,0,1] row_mask:0xf bank_mask:0xf
	v_mov_b32_dpp v73, v21 quad_perm:[2,3,0,1] row_mask:0xf bank_mask:0xf
	v_cndmask_b32_e64 v18, v18, v72, s[50:51]
	v_cndmask_b32_e64 v19, v19, v73, s[50:51]
	v_cndmask_b32_e64 v20, v74, v20, s[50:51]
	v_cndmask_b32_e64 v21, v75, v21, s[50:51]
	s_nop 1
	v_mov_b32_dpp v72, v15 quad_perm:[1,0,3,2] row_mask:0xf bank_mask:0xf
	v_mov_b32_dpp v73, v14 quad_perm:[1,0,3,2] row_mask:0xf bank_mask:0xf
	v_mov_b32_dpp v74, v17 quad_perm:[1,0,3,2] row_mask:0xf bank_mask:0xf
	v_mov_b32_dpp v75, v16 quad_perm:[1,0,3,2] row_mask:0xf bank_mask:0xf
	v_cndmask_b32_e64 v14, v14, v72, s[36:37]
	v_cndmask_b32_e64 v15, v73, v15, s[36:37]
	v_cndmask_b32_e64 v16, v16, v74, s[36:37]
	v_cndmask_b32_e64 v17, v75, v17, s[36:37]
	s_nop 1
	v_mov_b32_dpp v74, v14 quad_perm:[2,3,0,1] row_mask:0xf bank_mask:0xf
	v_mov_b32_dpp v75, v15 quad_perm:[2,3,0,1] row_mask:0xf bank_mask:0xf
	v_mov_b32_dpp v72, v16 quad_perm:[2,3,0,1] row_mask:0xf bank_mask:0xf
	v_mov_b32_dpp v73, v17 quad_perm:[2,3,0,1] row_mask:0xf bank_mask:0xf
	v_cndmask_b32_e64 v14, v14, v72, s[50:51]
	v_cndmask_b32_e64 v15, v15, v73, s[50:51]
	v_cndmask_b32_e64 v16, v74, v16, s[50:51]
	v_cndmask_b32_e64 v17, v75, v17, s[50:51]
	s_nop 1
	v_mov_b32_dpp v72, v11 quad_perm:[1,0,3,2] row_mask:0xf bank_mask:0xf
	v_mov_b32_dpp v73, v10 quad_perm:[1,0,3,2] row_mask:0xf bank_mask:0xf
	v_mov_b32_dpp v74, v13 quad_perm:[1,0,3,2] row_mask:0xf bank_mask:0xf
	v_mov_b32_dpp v75, v12 quad_perm:[1,0,3,2] row_mask:0xf bank_mask:0xf
	v_cndmask_b32_e64 v10, v10, v72, s[36:37]
	v_cndmask_b32_e64 v11, v73, v11, s[36:37]
	v_cndmask_b32_e64 v12, v12, v74, s[36:37]
	v_cndmask_b32_e64 v13, v75, v13, s[36:37]
	s_nop 1
	v_mov_b32_dpp v74, v10 quad_perm:[2,3,0,1] row_mask:0xf bank_mask:0xf
	v_mov_b32_dpp v75, v11 quad_perm:[2,3,0,1] row_mask:0xf bank_mask:0xf
	v_mov_b32_dpp v72, v12 quad_perm:[2,3,0,1] row_mask:0xf bank_mask:0xf
	v_mov_b32_dpp v73, v13 quad_perm:[2,3,0,1] row_mask:0xf bank_mask:0xf
	v_cndmask_b32_e64 v10, v10, v72, s[50:51]
	v_cndmask_b32_e64 v11, v11, v73, s[50:51]
	v_cndmask_b32_e64 v12, v74, v12, s[50:51]
	v_cndmask_b32_e64 v13, v75, v13, s[50:51]
	s_nop 1
	v_mov_b32_dpp v72, v7 quad_perm:[1,0,3,2] row_mask:0xf bank_mask:0xf
	v_mov_b32_dpp v73, v6 quad_perm:[1,0,3,2] row_mask:0xf bank_mask:0xf
	v_mov_b32_dpp v74, v9 quad_perm:[1,0,3,2] row_mask:0xf bank_mask:0xf
	v_mov_b32_dpp v75, v8 quad_perm:[1,0,3,2] row_mask:0xf bank_mask:0xf
	v_cndmask_b32_e64 v6, v6, v72, s[36:37]
	v_cndmask_b32_e64 v7, v73, v7, s[36:37]
	v_cndmask_b32_e64 v8, v8, v74, s[36:37]
	v_cndmask_b32_e64 v9, v75, v9, s[36:37]
	s_nop 1
	v_mov_b32_dpp v74, v6 quad_perm:[2,3,0,1] row_mask:0xf bank_mask:0xf
	v_mov_b32_dpp v75, v7 quad_perm:[2,3,0,1] row_mask:0xf bank_mask:0xf
	v_mov_b32_dpp v72, v8 quad_perm:[2,3,0,1] row_mask:0xf bank_mask:0xf
	v_mov_b32_dpp v73, v9 quad_perm:[2,3,0,1] row_mask:0xf bank_mask:0xf
	v_cndmask_b32_e64 v6, v6, v72, s[50:51]
	v_cndmask_b32_e64 v7, v7, v73, s[50:51]
	v_cndmask_b32_e64 v8, v74, v8, s[50:51]
	v_cndmask_b32_e64 v9, v75, v9, s[50:51]
	s_nop 1
	v_mov_b32_dpp v72, v3 quad_perm:[1,0,3,2] row_mask:0xf bank_mask:0xf
	v_mov_b32_dpp v73, v2 quad_perm:[1,0,3,2] row_mask:0xf bank_mask:0xf
	v_mov_b32_dpp v74, v5 quad_perm:[1,0,3,2] row_mask:0xf bank_mask:0xf
	v_mov_b32_dpp v75, v4 quad_perm:[1,0,3,2] row_mask:0xf bank_mask:0xf
	v_cndmask_b32_e64 v2, v2, v72, s[36:37]
	v_cndmask_b32_e64 v3, v73, v3, s[36:37]
	v_cndmask_b32_e64 v4, v4, v74, s[36:37]
	v_cndmask_b32_e64 v5, v75, v5, s[36:37]
	s_nop 1
	v_mov_b32_dpp v74, v2 quad_perm:[2,3,0,1] row_mask:0xf bank_mask:0xf
	v_mov_b32_dpp v75, v3 quad_perm:[2,3,0,1] row_mask:0xf bank_mask:0xf
	v_mov_b32_dpp v72, v4 quad_perm:[2,3,0,1] row_mask:0xf bank_mask:0xf
	v_mov_b32_dpp v73, v5 quad_perm:[2,3,0,1] row_mask:0xf bank_mask:0xf
	v_cndmask_b32_e64 v2, v2, v72, s[50:51]
	v_cndmask_b32_e64 v3, v3, v73, s[50:51]
	v_cndmask_b32_e64 v4, v74, v4, s[50:51]
	v_cndmask_b32_e64 v5, v75, v5, s[50:51]
	s_waitcnt lgkmcnt(0)
	v_cvt_pk_bf16_f32 v30, v30, v31
	v_cvt_pk_bf16_f32 v31, v32, v33
	ds_write_b64 v209, v[30:31] offset:0
	v_cvt_pk_bf16_f32 v26, v26, v27
	v_cvt_pk_bf16_f32 v27, v28, v29
	ds_write_b64 v210, v[26:27] offset:0
	v_cvt_pk_bf16_f32 v22, v22, v23
	v_cvt_pk_bf16_f32 v23, v24, v25
	ds_write_b64 v211, v[22:23] offset:0
	v_cvt_pk_bf16_f32 v18, v18, v19
	v_cvt_pk_bf16_f32 v19, v20, v21
	ds_write_b64 v212, v[18:19] offset:0
	v_cvt_pk_bf16_f32 v14, v14, v15
	v_cvt_pk_bf16_f32 v15, v16, v17
	ds_write_b64 v209, v[14:15] offset:2048
	v_cvt_pk_bf16_f32 v10, v10, v11
	v_cvt_pk_bf16_f32 v11, v12, v13
	ds_write_b64 v210, v[10:11] offset:2048
	v_cvt_pk_bf16_f32 v6, v6, v7
	v_cvt_pk_bf16_f32 v7, v8, v9
	ds_write_b64 v211, v[6:7] offset:2048
	v_cvt_pk_bf16_f32 v2, v2, v3
	v_cvt_pk_bf16_f32 v3, v4, v5
	ds_write_b64 v212, v[2:3] offset:2048
	s_waitcnt lgkmcnt(0)
	ds_read_b128 v[76:79], v213 offset:0
	ds_read_b128 v[80:83], v213 offset:1024
	ds_read_b128 v[84:87], v213 offset:2048
	ds_read_b128 v[88:91], v213 offset:3072
	s_waitcnt lgkmcnt(3)
	v_add_u32_e32 v216, 0x40000, v214
	global_store_dwordx4 v216, v[76:79], s[16:17] sc1
	s_waitcnt lgkmcnt(2)
	v_add_u32_e32 v216, 0x50000, v214
	global_store_dwordx4 v216, v[80:83], s[16:17] sc1
	s_waitcnt lgkmcnt(1)
	v_add_u32_e32 v216, 0x60000, v214
	global_store_dwordx4 v216, v[84:87], s[16:17] sc1
	s_waitcnt lgkmcnt(0)
	v_add_u32_e32 v216, 0x70000, v214
	global_store_dwordx4 v216, v[88:91], s[16:17] sc1
	s_nop 1
	s_and_b64 vcc, exec, s[34:35]
	s_cbranch_vccnz .Lrelu2_nost2
	s_mov_b64 s[16:17], 0x100
	s_mov_b64 s[36:37], 0x4100
	s_mov_b64 s[38:39], 0x8100
	v_lshl_add_u64 v[70:71], v[66:67], 0, s[16:17]
	s_add_i32 m0, s8, 0x18000
	s_nop 0
	global_load_lds_dwordx4 v[70:71], off sc1
	v_lshl_add_u64 v[70:71], v[66:67], 0, s[36:37]
	s_mov_b32 m0, s45
	s_nop 0
	global_load_lds_dwordx4 v[70:71], off sc1
	v_lshl_add_u64 v[70:71], v[66:67], 0, s[38:39]
	s_mov_b32 m0, s46
	s_mov_b64 s[38:39], 0xc100
	global_load_lds_dwordx4 v[70:71], off sc1
	v_lshl_add_u64 v[66:67], v[66:67], 0, s[38:39]
	s_mov_b32 m0, s47
	s_nop 0
	global_load_lds_dwordx4 v[66:67], off sc1
	v_lshl_add_u64 v[66:67], v[68:69], 0, s[16:17]
	s_add_i32 m0, s9, 0x20000
	s_nop 0
	global_load_lds_dwordx4 v[66:67], off sc1
	v_lshl_add_u64 v[66:67], v[68:69], 0, s[36:37]
	s_mov_b32 m0, s48
	s_nop 0
	global_load_lds_dwordx4 v[66:67], off sc1
.Lrelu2_nost2:
	s_mov_b64 s[38:39], -1
	s_and_b64 vcc, exec, s[34:35]
	s_cbranch_vccz .Lm1_cont
	s_waitcnt vmcnt(0)
	s_barrier
	v_readfirstlane_b32 s53, v137
	s_cmp_lt_u32 s53, 64
	s_cbranch_scc0 .Lm1rec_skip_e
	v_readlane_b32 s52, v255, 40
	s_add_i32 s52, s52, 0x5d0e2000
	s_add_i32 s53, s66, -1
	v_mov_b32_e32 v226, s53
	v_mov_b32_e32 v228, s52
	v_mov_b32_e32 v229, s52
	v_mov_b32_e32 v230, s52
	v_mov_b32_e32 v231, s52
	s_add_u32 s64, s94, 0xcbc9000
	s_addc_u32 s65, s95, 0
	s_mov_b64 exec, 1
	global_store_dwordx4 v226, v[228:231], s[64:65] sc1
	s_mov_b64 exec, -1
.Lm1rec_skip_e:
	s_mov_b32 s66, 0
	s_branch .LBB0_89
.Lm1_cont:
.LBB0_81:
	s_mul_hi_i32 s6, s49, 0x2aaaaaab
	s_lshr_b32 s14, s6, 31
	s_ashr_i32 s6, s6, 2
	s_add_i32 s6, s6, s14
	s_mul_i32 s14, s6, 24
	s_sub_i32 s14, s49, s14
	s_lshl_b32 s26, s14, 8
	s_lshl_b32 s22, s6, 7
	s_ashr_i32 s27, s26, 31
	s_ashr_i32 s23, s22, 31
	s_lshl_b64 s[34:35], s[26:27], 11
	s_lshl_b64 s[36:37], s[22:23], 11
	s_and_b64 vcc, exec, s[38:39]
	s_cbranch_vccnz .Lrelu2_pf
	v_readlane_b32 s52, v255, 40
	s_add_i32 s52, s52, 0x5d0e1000
	s_lshl_b32 s53, s14, 7
	s_add_u32 s64, s94, 0xcbc8000
	s_addc_u32 s65, s95, 0
	v_and_b32_e32 v226, 7, v137
	v_lshlrev_b32_e32 v226, 4, v226
	v_add_u32_e32 v226, s53, v226
	s_mov_b32 s53, 0x100000

.LBB0_84:
	s_mul_hi_u32 s34, s27, 0xaaaaaaab
	s_lshr_b32 s34, s34, 1
	s_mul_i32 s34, s34, 0x24000
	s_waitcnt lgkmcnt(0)
	v_mfma_f32_16x16x32_bf16 v[82:85], v[26:29], v[22:25], v[82:85]
	v_add_u32_e32 v191, s14, v99
	s_mul_hi_u32 s35, s19, 0xaaaaaaab
	s_lshr_b32 s35, s35, 1
	v_mfma_f32_16x16x32_bf16 v[78:81], v[26:29], v[18:21], v[78:81]
	s_mul_i32 s35, s35, 0x24000
	v_subrev_u32_e32 v180, s35, v128
	v_subrev_u32_e32 v181, s35, v129
	v_mfma_f32_16x16x32_bf16 v[74:77], v[26:29], v[10:13], v[74:77]
	v_subrev_u32_e32 v182, s35, v130
	v_mfma_f32_16x16x32_bf16 v[70:73], v[26:29], v[6:9], v[70:73]
	v_subrev_u32_e32 v26, s34, v127
	v_mfma_f32_16x16x32_bf16 v[66:69], v[14:17], v[22:25], v[66:69]
	v_mfma_f32_16x16x32_bf16 v[62:65], v[14:17], v[18:21], v[62:65]
	v_mfma_f32_16x16x32_bf16 v[58:61], v[14:17], v[10:13], v[58:61]
	v_mfma_f32_16x16x32_bf16 v[54:57], v[14:17], v[6:9], v[54:57]
	v_subrev_u32_e32 v14, s34, v131
	v_add_u32_e32 v16, v191, v26
	v_add_u32_e32 v14, v191, v14
	v_mfma_f32_16x16x32_bf16 v[38:41], v[30:33], v[22:25], v[38:41]
	v_subrev_u32_e32 v15, s35, v132
	v_mfma_f32_16x16x32_bf16 v[50:53], v[2:5], v[22:25], v[50:53]
	ds_read_b128 v[22:25], v16
	ds_read_b128 v[176:179], v16 offset:2048
	ds_read_b128 v[202:205], v16 offset:4096
	ds_read_b128 v[206:209], v16 offset:6144
	ds_read_b128 v[210:213], v14 offset:32768
	ds_read_b128 v[214:217], v14 offset:34816
	ds_read_b128 v[218:221], v14 offset:36864
	ds_read_b128 v[222:225], v14 offset:38912
	v_mfma_f32_16x16x32_bf16 v[90:93], v[30:33], v[18:21], v[90:93]
	v_mfma_f32_16x16x32_bf16 v[86:89], v[30:33], v[10:13], v[86:89]
	v_mfma_f32_16x16x32_bf16 v[94:97], v[30:33], v[6:9], v[94:97]
	v_mfma_f32_16x16x32_bf16 v[46:49], v[2:5], v[18:21], v[46:49]
	v_mfma_f32_16x16x32_bf16 v[42:45], v[2:5], v[10:13], v[42:45]
	v_mfma_f32_16x16x32_bf16 v[34:37], v[2:5], v[6:9], v[34:37]
	s_add_i32 s34, s6, 4
	s_mul_i32 s35, s34, 0xab
	s_bfe_u32 s35, s35, 0x70009
	s_mul_i32 s35, s35, 3
	s_sub_i32 s34, s34, s35
	s_and_b32 s34, s34, 0xff
	s_mul_i32 s36, s34, 0xc000
	s_waitcnt vmcnt(6)
	v_add_u32_e32 v2, v191, v15
	v_add_u32_e32 v6, v191, v182
	s_waitcnt lgkmcnt(0)
	v_mfma_f32_16x16x32_bf16 v[82:85], v[176:179], v[210:213], v[82:85]
	s_add_i32 s34, s36, s8
	s_waitcnt lgkmcnt(0)
	s_barrier
	s_cmp_eq_u32 s66, 0
	s_cbranch_scc1 .Lm1_nopend
	v_readfirstlane_b32 s53, v137
	s_cmp_lt_u32 s53, 64
	s_cbranch_scc0 .Lm1rec_skip_l
	v_readlane_b32 s52, v255, 40
	s_add_i32 s52, s52, 0x5d0e2000
	s_add_i32 s53, s66, -1
	v_mov_b32_e32 v226, s53
	v_mov_b32_e32 v228, s52
	v_mov_b32_e32 v229, s52
	v_mov_b32_e32 v230, s52
	v_mov_b32_e32 v231, s52
	s_add_u32 s64, s94, 0xcbc9000
	s_addc_u32 s65, s95, 0
	s_mov_b64 exec, 1
	global_store_dwordx4 v226, v[228:231], s[64:65] sc1
	s_mov_b64 exec, -1
.Lm1rec_skip_l:
	s_mov_b32 s66, 0
.Lm1_nopend:
	v_mfma_f32_16x16x32_bf16 v[78:81], v[176:179], v[214:217], v[78:81]
	ds_read_b128 v[30:33], v2
	ds_read_b128 v[26:29], v2 offset:2048
	ds_read_b128 v[14:17], v2 offset:4096
	ds_read_b128 v[2:5], v2 offset:6144
	v_add_u32_e32 v7, v191, v181
	v_mfma_f32_16x16x32_bf16 v[74:77], v[176:179], v[218:221], v[74:77]
	s_mov_b32 m0, s34
	s_add_i32 s36, s36, s9
	s_add_i32 s27, s27, 1
	v_mfma_f32_16x16x32_bf16 v[70:73], v[176:179], v[222:225], v[70:73]
	v_lshl_add_u64 v[176:177], v[116:117], 0, v[100:101]
	v_lshl_add_u64 v[178:179], v[176:177], 0, s[84:85]
	v_mfma_f32_16x16x32_bf16 v[38:41], v[22:25], v[210:213], v[38:41]
	v_mfma_f32_16x16x32_bf16 v[90:93], v[22:25], v[214:217], v[90:93]
	v_mfma_f32_16x16x32_bf16 v[86:89], v[22:25], v[218:221], v[86:89]
	v_mfma_f32_16x16x32_bf16 v[94:97], v[22:25], v[222:225], v[94:97]
	ds_read_b128 v[22:25], v6
	ds_read_b128 v[18:21], v7
	v_add_u32_e32 v6, v191, v180
	ds_read_b128 v[10:13], v6
	ds_read_b128 v[6:9], v6 offset:2048
	global_load_lds_dwordx4 v[178:179], off sc1
	v_lshl_add_u64 v[178:179], v[176:177], 0, s[76:77]
	s_add_i32 m0, s34, 0x400
	v_mfma_f32_16x16x32_bf16 v[66:69], v[202:205], v[210:213], v[66:69]
	global_load_lds_dwordx4 v[178:179], off sc1
	v_lshl_add_u64 v[178:179], v[176:177], 0, s[54:55]
	s_add_i32 m0, s34, 0x800
	v_lshl_add_u64 v[176:177], v[176:177], 0, s[68:69]
	global_load_lds_dwordx4 v[178:179], off sc1
	s_add_i32 m0, s34, 0xc00
	s_mov_b64 s[34:35], 0x2300180
	global_load_lds_dwordx4 v[176:177], off sc1
	v_lshl_add_u64 v[176:177], v[118:119], 0, v[100:101]
	v_lshl_add_u64 v[178:179], v[176:177], 0, s[34:35]
	s_add_i32 m0, s36, 0x8000
	s_mov_b64 s[34:35], 0x2304180
	global_load_lds_dwordx4 v[178:179], off sc1
	v_lshl_add_u64 v[176:177], v[176:177], 0, s[34:35]
	s_add_i32 m0, s36, 0x8400
	v_mfma_f32_16x16x32_bf16 v[62:65], v[202:205], v[214:217], v[62:65]
	global_load_lds_dwordx4 v[176:177], off sc1
	v_mfma_f32_16x16x32_bf16 v[58:61], v[202:205], v[218:221], v[58:61]
	v_mfma_f32_16x16x32_bf16 v[54:57], v[202:205], v[222:225], v[54:57]
	v_mfma_f32_16x16x32_bf16 v[50:53], v[206:209], v[210:213], v[50:53]
	v_mfma_f32_16x16x32_bf16 v[46:49], v[206:209], v[214:217], v[46:49]
	v_mfma_f32_16x16x32_bf16 v[42:45], v[206:209], v[218:221], v[42:45]
	v_mfma_f32_16x16x32_bf16 v[34:37], v[206:209], v[222:225], v[34:37]
	s_add_i32 s6, s6, 1
	s_add_i32 s14, s14, 0xc000
	s_add_i32 s19, s19, 1
	v_lshl_add_u64 v[116:117], v[116:117], 0, s[2:3]
	s_cmp_eq_u32 s14, 0x9c000
	v_lshl_add_u64 v[118:119], v[118:119], 0, s[2:3]
	s_cbranch_scc0 .LBB0_84
	s_waitcnt lgkmcnt(0)
	v_mfma_f32_16x16x32_bf16 v[38:41], v[30:33], v[22:25], v[38:41]
	v_mfma_f32_16x16x32_bf16 v[90:93], v[30:33], v[18:21], v[90:93]
	v_mfma_f32_16x16x32_bf16 v[86:89], v[30:33], v[10:13], v[86:89]
	v_mfma_f32_16x16x32_bf16 v[30:33], v[30:33], v[6:9], v[94:97]
	v_mfma_f32_16x16x32_bf16 v[82:85], v[26:29], v[22:25], v[82:85]
	v_mfma_f32_16x16x32_bf16 v[78:81], v[26:29], v[18:21], v[78:81]
	v_mfma_f32_16x16x32_bf16 v[74:77], v[26:29], v[10:13], v[74:77]
	v_mfma_f32_16x16x32_bf16 v[26:29], v[26:29], v[6:9], v[70:73]
	v_mfma_f32_16x16x32_bf16 v[66:69], v[14:17], v[22:25], v[66:69]
	v_mfma_f32_16x16x32_bf16 v[62:65], v[14:17], v[18:21], v[62:65]
	v_mfma_f32_16x16x32_bf16 v[58:61], v[14:17], v[10:13], v[58:61]
	v_mfma_f32_16x16x32_bf16 v[14:17], v[14:17], v[6:9], v[54:57]
	v_mfma_f32_16x16x32_bf16 v[22:25], v[2:5], v[22:25], v[50:53]
	v_mfma_f32_16x16x32_bf16 v[18:21], v[2:5], v[18:21], v[46:49]
	s_nop 2
	ds_read_b128 v[46:49], v163
	ds_read_b128 v[50:53], v164 offset:2048
	ds_read_b128 v[54:57], v164 offset:4096
	ds_read_b128 v[70:73], v164 offset:6144
	v_mfma_f32_16x16x32_bf16 v[10:13], v[2:5], v[10:13], v[42:45]
	s_nop 2
	ds_read_b128 v[42:45], v165 offset:32768
	ds_read_b128 v[94:97], v166 offset:34816
	ds_read_b128 v[116:119], v166 offset:36864
	ds_read_b128 v[176:179], v166 offset:38912
	v_mfma_f32_16x16x32_bf16 v[2:5], v[2:5], v[6:9], v[34:37]
	s_waitcnt lgkmcnt(0)
	v_mfma_f32_16x16x32_bf16 v[6:9], v[46:49], v[42:45], v[38:41]
	s_waitcnt vmcnt(6)
	s_waitcnt lgkmcnt(0)
	s_barrier
	v_mfma_f32_16x16x32_bf16 v[34:37], v[46:49], v[94:97], v[90:93]
	v_mfma_f32_16x16x32_bf16 v[38:41], v[46:49], v[116:119], v[86:89]
	s_nop 1
	v_add_u32_e32 v90, 0x20800, v161
	v_mfma_f32_16x16x32_bf16 v[30:33], v[46:49], v[176:179], v[30:33]
	v_mfma_f32_16x16x32_bf16 v[46:49], v[50:53], v[42:45], v[82:85]
	v_mfma_f32_16x16x32_bf16 v[78:81], v[50:53], v[94:97], v[78:81]
	v_mfma_f32_16x16x32_bf16 v[74:77], v[50:53], v[116:119], v[74:77]
	v_mfma_f32_16x16x32_bf16 v[26:29], v[50:53], v[176:179], v[26:29]
	v_mfma_f32_16x16x32_bf16 v[50:53], v[54:57], v[42:45], v[66:69]
	v_mfma_f32_16x16x32_bf16 v[62:65], v[54:57], v[94:97], v[62:65]
	v_mfma_f32_16x16x32_bf16 v[58:61], v[54:57], v[116:119], v[58:61]
	v_mfma_f32_16x16x32_bf16 v[14:17], v[54:57], v[176:179], v[14:17]
	v_add_u32_e32 v54, v126, v120
	ds_read_b128 v[54:57], v54
	ds_read_b128 v[66:69], v167 offset:2048
	v_mfma_f32_16x16x32_bf16 v[18:21], v[70:73], v[94:97], v[18:21]
	v_add_u32_e32 v94, 0x21000, v161
	v_mfma_f32_16x16x32_bf16 v[10:13], v[70:73], v[116:119], v[10:13]
	v_add_u32_e32 v116, 0x21800, v161
	v_mfma_f32_16x16x32_bf16 v[22:25], v[70:73], v[42:45], v[22:25]
	ds_read_b128 v[42:45], v167 offset:4096
	ds_read_b128 v[82:85], v167 offset:6144
	ds_read_b128 v[86:89], v168
	ds_read_b128 v[90:93], v90
	ds_read_b128 v[94:97], v94
	ds_read_b128 v[116:119], v116
	v_mfma_f32_16x16x32_bf16 v[2:5], v[70:73], v[176:179], v[2:5]
	s_waitcnt lgkmcnt(0)
	v_mfma_f32_16x16x32_bf16 v[50:53], v[42:45], v[86:89], v[50:53]
	v_mfma_f32_16x16x32_bf16 v[62:65], v[42:45], v[90:93], v[62:65]
	v_mfma_f32_16x16x32_bf16 v[58:61], v[42:45], v[94:97], v[58:61]
	v_mfma_f32_16x16x32_bf16 v[14:17], v[42:45], v[116:119], v[14:17]
	v_add_u32_e32 v42, v126, v124
	v_mfma_f32_16x16x32_bf16 v[6:9], v[54:57], v[86:89], v[6:9]
	v_mfma_f32_16x16x32_bf16 v[34:37], v[54:57], v[90:93], v[34:37]
	v_mfma_f32_16x16x32_bf16 v[38:41], v[54:57], v[94:97], v[38:41]
	v_mfma_f32_16x16x32_bf16 v[30:33], v[54:57], v[116:119], v[30:33]
	v_mfma_f32_16x16x32_bf16 v[46:49], v[66:69], v[86:89], v[46:49]
	v_mfma_f32_16x16x32_bf16 v[54:57], v[66:69], v[90:93], v[78:81]
	v_mfma_f32_16x16x32_bf16 v[70:73], v[66:69], v[94:97], v[74:77]
	v_mfma_f32_16x16x32_bf16 v[26:29], v[66:69], v[116:119], v[26:29]
	ds_read_b128 v[42:45], v42
	ds_read_b128 v[66:69], v169
	ds_read_b128 v[74:77], v170
	ds_read_b128 v[78:81], v171
	v_mfma_f32_16x16x32_bf16 v[22:25], v[82:85], v[86:89], v[22:25]
	v_mfma_f32_16x16x32_bf16 v[18:21], v[82:85], v[90:93], v[18:21]
	v_mfma_f32_16x16x32_bf16 v[10:13], v[82:85], v[94:97], v[10:13]
	ds_read_b128 v[86:89], v172
	ds_read_b128 v[90:93], v173
	ds_read_b128 v[94:97], v174
	ds_read_b128 v[176:179], v175
	v_mfma_f32_16x16x32_bf16 v[2:5], v[82:85], v[116:119], v[2:5]
	s_waitcnt vmcnt(0)
	s_waitcnt lgkmcnt(0)
	v_mfma_f32_16x16x32_bf16 v[6:9], v[42:45], v[86:89], v[6:9]
	s_waitcnt lgkmcnt(0)
	s_barrier
	v_mfma_f32_16x16x32_bf16 v[34:37], v[42:45], v[90:93], v[34:37]
	v_mfma_f32_16x16x32_bf16 v[38:41], v[42:45], v[94:97], v[38:41]
	v_mfma_f32_16x16x32_bf16 v[30:33], v[42:45], v[176:179], v[30:33]
	v_mfma_f32_16x16x32_bf16 v[42:45], v[66:69], v[86:89], v[46:49]
	v_mfma_f32_16x16x32_bf16 v[46:49], v[66:69], v[90:93], v[54:57]
	v_mfma_f32_16x16x32_bf16 v[54:57], v[66:69], v[94:97], v[70:73]
	v_mfma_f32_16x16x32_bf16 v[26:29], v[66:69], v[176:179], v[26:29]
	v_mfma_f32_16x16x32_bf16 v[50:53], v[74:77], v[86:89], v[50:53]
	v_mfma_f32_16x16x32_bf16 v[62:65], v[74:77], v[90:93], v[62:65]
	v_mfma_f32_16x16x32_bf16 v[58:61], v[74:77], v[94:97], v[58:61]
	v_mfma_f32_16x16x32_bf16 v[14:17], v[74:77], v[176:179], v[14:17]
	ds_read_b128 v[66:69], v161 offset:38912
	ds_read_b128 v[70:73], v161 offset:36864
	ds_read_b128 v[74:77], v161 offset:34816
	ds_read_b128 v[82:85], v135 offset:32768
	v_mfma_f32_16x16x32_bf16 v[22:25], v[78:81], v[86:89], v[22:25]
	v_mfma_f32_16x16x32_bf16 v[18:21], v[78:81], v[90:93], v[18:21]
	v_mfma_f32_16x16x32_bf16 v[10:13], v[78:81], v[94:97], v[10:13]
	ds_read_b128 v[86:89], v134 offset:6144
	ds_read_b128 v[90:93], v134 offset:4096
	ds_read_b128 v[94:97], v134 offset:2048
	ds_read_b128 v[116:119], v133
	v_mfma_f32_16x16x32_bf16 v[2:5], v[78:81], v[176:179], v[2:5]
	s_waitcnt lgkmcnt(0)
	v_mfma_f32_16x16x32_bf16 v[78:81], v[94:97], v[74:77], v[46:49]
	s_nop 2
	v_add_u32_e32 v46, v105, v124
	v_mfma_f32_16x16x32_bf16 v[6:9], v[116:119], v[82:85], v[6:9]
	v_add_u32_e32 v47, v121, v124
	v_mfma_f32_16x16x32_bf16 v[34:37], v[116:119], v[74:77], v[34:37]
	v_mfma_f32_16x16x32_bf16 v[38:41], v[116:119], v[70:73], v[38:41]
	v_mfma_f32_16x16x32_bf16 v[30:33], v[116:119], v[66:69], v[30:33]
	v_mfma_f32_16x16x32_bf16 v[42:45], v[94:97], v[82:85], v[42:45]
	v_mfma_f32_16x16x32_bf16 v[116:119], v[94:97], v[70:73], v[54:57]
	v_mfma_f32_16x16x32_bf16 v[26:29], v[94:97], v[66:69], v[26:29]
	v_mfma_f32_16x16x32_bf16 v[94:97], v[90:93], v[82:85], v[50:53]
	v_mfma_f32_16x16x32_bf16 v[176:179], v[90:93], v[74:77], v[62:65]
	v_mfma_f32_16x16x32_bf16 v[202:205], v[90:93], v[70:73], v[58:61]
	v_mfma_f32_16x16x32_bf16 v[14:17], v[90:93], v[66:69], v[14:17]
	v_mfma_f32_16x16x32_bf16 v[82:85], v[86:89], v[82:85], v[22:25]
	s_nop 2
	ds_read_b128 v[22:25], v46
	ds_read_b128 v[90:93], v47 offset:2048
	v_add_u32_e32 v46, v122, v124
	v_mfma_f32_16x16x32_bf16 v[74:77], v[86:89], v[74:77], v[18:21]
	s_nop 2
	ds_read_b128 v[18:21], v47 offset:4096
	ds_read_b128 v[206:209], v47 offset:6144
	v_add_u32_e32 v47, v123, v124
	v_mfma_f32_16x16x32_bf16 v[70:73], v[86:89], v[70:73], v[10:13]
	s_nop 2
	ds_read_b128 v[10:13], v46 offset:32768
	ds_read_b128 v[210:213], v47 offset:34816
	ds_read_b128 v[214:217], v47 offset:36864
	ds_read_b128 v[218:221], v47 offset:38912
	v_mfma_f32_16x16x32_bf16 v[2:5], v[86:89], v[66:69], v[2:5]
	s_waitcnt lgkmcnt(0)
	v_mfma_f32_16x16x32_bf16 v[62:65], v[22:25], v[10:13], v[6:9]
	s_waitcnt vmcnt(0)
	s_waitcnt lgkmcnt(0)
	s_barrier
	v_mfma_f32_16x16x32_bf16 v[58:61], v[22:25], v[210:213], v[34:37]
	v_mfma_f32_16x16x32_bf16 v[54:57], v[22:25], v[214:217], v[38:41]
	v_mfma_f32_16x16x32_bf16 v[50:53], v[22:25], v[218:221], v[30:33]
	v_mfma_f32_16x16x32_bf16 v[46:49], v[90:93], v[10:13], v[42:45]
	v_mfma_f32_16x16x32_bf16 v[42:45], v[90:93], v[210:213], v[78:81]
	v_mfma_f32_16x16x32_bf16 v[38:41], v[90:93], v[214:217], v[116:119]
	v_mfma_f32_16x16x32_bf16 v[34:37], v[90:93], v[218:221], v[26:29]
	v_mfma_f32_16x16x32_bf16 v[30:33], v[18:21], v[10:13], v[94:97]
	v_mfma_f32_16x16x32_bf16 v[26:29], v[18:21], v[210:213], v[176:179]
	v_mfma_f32_16x16x32_bf16 v[22:25], v[18:21], v[214:217], v[202:205]
	v_mfma_f32_16x16x32_bf16 v[18:21], v[18:21], v[218:221], v[14:17]
	v_mfma_f32_16x16x32_bf16 v[14:17], v[206:209], v[10:13], v[82:85]
	v_mfma_f32_16x16x32_bf16 v[10:13], v[206:209], v[210:213], v[74:77]
	v_mfma_f32_16x16x32_bf16 v[6:9], v[206:209], v[214:217], v[70:73]
	v_mfma_f32_16x16x32_bf16 v[2:5], v[206:209], v[218:221], v[2:5]
	s_waitcnt lgkmcnt(0)
	s_barrier
	s_load_dword s6, s[78:79], 0x0
	s_waitcnt lgkmcnt(0)
	s_add_i32 s49, s6, s49
	s_cmpk_gt_i32 s49, 0x2ff
	s_cselect_b64 s[34:35], -1, 0
	s_cmpk_lt_i32 s49, 0x300
	s_cbranch_scc0 .LBB0_80
	s_mul_hi_i32 s6, s49, 0x2aaaaaab
	s_lshr_b32 s14, s6, 31
	s_ashr_i32 s6, s6, 2
	s_add_i32 s6, s6, s14
	s_mul_i32 s14, s6, 24
	s_sub_i32 s14, s49, s14
	v_readlane_b32 s52, v255, 40
	s_add_i32 s52, s52, 0x5d0e1000
	s_lshl_b32 s53, s14, 7
	s_add_u32 s64, s94, 0xcbc8000
	s_addc_u32 s65, s95, 0
	v_and_b32_e32 v226, 7, v137
	v_lshlrev_b32_e32 v226, 4, v226
	v_add_u32_e32 v226, s53, v226
	s_mov_b32 s53, 0x100000

.LBB0_412:
	s_mul_hi_i32 s13, s70, 0x2aaaaaab
	s_lshr_b32 s14, s13, 31
	s_ashr_i32 s35, s13, 2
	s_add_i32 s35, s35, s14
	s_mul_i32 s13, s35, 24
	s_sub_i32 s60, s70, s13
	s_and_b32 s13, s60, 7
	s_lshl_b32 s13, s13, 10
	v_readlane_b32 s52, v255, 40
	s_add_i32 s52, s52, 0x5d0e2000
	s_lshl_b32 s54, s60, 9
	s_add_u32 s50, s94, 0xcbc9000
	s_addc_u32 s51, s95, 0
	v_and_b32_e32 v226, 31, v137
	v_lshlrev_b32_e32 v226, 4, v226
	v_add_u32_e32 v226, s54, v226
	s_mov_b32 s53, 0x100000
.Lln2dep_poll:
	global_load_dwordx4 v[228:231], v226, s[50:51] sc1
	s_waitcnt vmcnt(0)
	v_cmp_ne_u32_e32 vcc, s52, v228
	s_cbranch_vccz .Lln2dep_ok
	s_sleep 1
	s_add_i32 s53, s53, -1
	s_cmp_lg_u32 s53, 0
	s_cbranch_scc1 .Lln2dep_poll
.Lln2dep_ok:
	s_lshl_b32 s22, s60, 8
	s_ashr_i32 s23, s22, 31
	s_lshl_b64 s[36:37], s[22:23], 13
	s_or_b32 s36, s36, s13
	s_mov_b32 m0, s8
	v_lshl_add_u64 v[2:3], v[100:101], 0, s[36:37]
	s_mov_b64 s[50:51], 0x10000
	s_lshl_b32 s26, s35, 7
	global_load_lds_dwordx4 v[2:3], off sc1
	v_lshl_add_u64 v[6:7], v[2:3], 0, s[50:51]
	s_add_i32 m0, s8, 0x400
	s_mov_b64 s[52:53], 0x20000
	s_ashr_i32 s27, s26, 31
	global_load_lds_dwordx4 v[6:7], off sc1
	v_lshl_add_u64 v[6:7], v[2:3], 0, s[52:53]
	s_add_i32 m0, s8, 0x800
	s_mov_b64 s[52:53], 0x30000
	s_lshl_b64 s[48:49], s[26:27], 13
	s_or_b32 s48, s48, s13
	global_load_lds_dwordx4 v[6:7], off sc1
	v_lshl_add_u64 v[6:7], v[2:3], 0, s[52:53]
	s_add_i32 m0, s8, 0xc00
	v_lshl_add_u64 v[4:5], v[102:103], 0, s[48:49]
	global_load_lds_dwordx4 v[6:7], off sc1
	s_add_i32 m0, s9, 0x8000
	v_lshl_add_u64 v[6:7], v[4:5], 0, s[50:51]
	global_load_lds_dwordx4 v[4:5], off sc1
	s_add_i32 m0, s9, 0x8400
	s_mov_b64 s[50:51], 0x10080
	global_load_lds_dwordx4 v[6:7], off sc1
	v_lshl_add_u64 v[6:7], v[2:3], 0, s[2:3]
	s_add_i32 m0, s8, 0xc000
	s_mov_b64 s[52:53], 0x20080
	global_load_lds_dwordx4 v[6:7], off sc1
	v_lshl_add_u64 v[6:7], v[2:3], 0, s[50:51]
	s_add_i32 m0, s8, 0xc400
	s_mov_b64 s[54:55], 0x10100
	global_load_lds_dwordx4 v[6:7], off sc1
	v_lshl_add_u64 v[6:7], v[2:3], 0, s[52:53]
	s_add_i32 m0, s8, 0xc800
	s_mov_b64 s[52:53], 0x30080
	global_load_lds_dwordx4 v[6:7], off sc1
	v_lshl_add_u64 v[6:7], v[2:3], 0, s[52:53]
	s_add_i32 m0, s8, 0xcc00
	s_mov_b64 s[52:53], 0x20100
	global_load_lds_dwordx4 v[6:7], off sc1
	v_lshl_add_u64 v[6:7], v[4:5], 0, s[2:3]
	s_add_i32 m0, s9, 0x14000
	v_add_u32_e32 v172, v114, v115
	global_load_lds_dwordx4 v[6:7], off sc1
	v_lshl_add_u64 v[6:7], v[4:5], 0, s[50:51]
	s_add_i32 m0, s9, 0x14400
	s_mov_b64 s[50:51], 0x100
	global_load_lds_dwordx4 v[6:7], off sc1
	v_lshl_add_u64 v[6:7], v[2:3], 0, s[50:51]
	s_add_i32 m0, s8, 0x18000
	v_add_u32_e32 v173, v116, v115
	global_load_lds_dwordx4 v[6:7], off sc1
	v_lshl_add_u64 v[6:7], v[2:3], 0, s[54:55]
	s_add_i32 m0, s8, 0x18400
	v_mov_b32_e32 v38, 0
	global_load_lds_dwordx4 v[6:7], off sc1
	v_lshl_add_u64 v[6:7], v[2:3], 0, s[52:53]
	s_add_i32 m0, s8, 0x18800
	s_mov_b64 s[52:53], 0x30100
	global_load_lds_dwordx4 v[6:7], off sc1
	v_lshl_add_u64 v[2:3], v[2:3], 0, s[52:53]
	s_add_i32 m0, s8, 0x18c00
	v_lshl_add_u64 v[108:109], v[104:105], 0, s[36:37]
	global_load_lds_dwordx4 v[2:3], off sc1
	v_lshl_add_u64 v[2:3], v[4:5], 0, s[50:51]
	s_add_i32 m0, s9, 0x20000
	v_lshl_add_u64 v[110:111], v[106:107], 0, s[48:49]
	global_load_lds_dwordx4 v[2:3], off sc1
	v_lshl_add_u64 v[2:3], v[4:5], 0, s[54:55]
	s_add_i32 m0, s9, 0x20400
	s_lshr_b32 s55, s13, 7
	s_sub_i32 s55, 61, s55
	s_mov_b32 s13, -1
	global_load_lds_dwordx4 v[2:3], off sc1
	s_waitcnt vmcnt(12)
	s_waitcnt lgkmcnt(0)
	s_barrier
	ds_read_b128 v[30:33], v172
	ds_read_b128 v[26:29], v173 offset:2048
	s_waitcnt vmcnt(0)
	ds_read_b128 v[14:17], v173 offset:4096
	ds_read_b128 v[2:5], v173 offset:6144
	ds_read_b128 v[22:25], v161 offset:32768
	ds_read_b128 v[18:21], v164 offset:34816
	ds_read_b128 v[10:13], v164 offset:36864
	ds_read_b128 v[6:9], v164 offset:38912
	s_mov_b32 s14, 0
	s_mov_b32 s19, 1
	s_mov_b32 s23, 0
	v_mov_b32_e32 v39, v38
	v_mov_b32_e32 v40, v38
	v_mov_b32_e32 v41, v38
	v_mov_b32_e32 v42, v38
	v_mov_b32_e32 v43, v38
	v_mov_b32_e32 v44, v38
	v_mov_b32_e32 v45, v38
	v_mov_b32_e32 v46, v38
	v_mov_b32_e32 v47, v38
	v_mov_b32_e32 v48, v38
	v_mov_b32_e32 v49, v38
	v_mov_b32_e32 v50, v38
	v_mov_b32_e32 v51, v38
	v_mov_b32_e32 v52, v38
	v_mov_b32_e32 v53, v38
	v_mov_b32_e32 v54, v38
	v_mov_b32_e32 v55, v38
	v_mov_b32_e32 v56, v38
	v_mov_b32_e32 v57, v38
	v_mov_b32_e32 v58, v38
	v_mov_b32_e32 v59, v38
	v_mov_b32_e32 v60, v38
	v_mov_b32_e32 v61, v38
	v_mov_b32_e32 v62, v38
	v_mov_b32_e32 v63, v38
	v_mov_b32_e32 v64, v38
	v_mov_b32_e32 v65, v38
	v_mov_b32_e32 v66, v38
	v_mov_b32_e32 v67, v38
	v_mov_b32_e32 v68, v38
	v_mov_b32_e32 v69, v38
	v_mov_b32_e32 v78, v38
	v_mov_b32_e32 v79, v38
	v_mov_b32_e32 v80, v38
	v_mov_b32_e32 v81, v38
	v_mov_b32_e32 v70, v38
	v_mov_b32_e32 v71, v38
	v_mov_b32_e32 v72, v38
	v_mov_b32_e32 v73, v38
	v_mov_b32_e32 v74, v38
	v_mov_b32_e32 v75, v38
	v_mov_b32_e32 v76, v38
	v_mov_b32_e32 v77, v38
	v_mov_b32_e32 v34, v38
	v_mov_b32_e32 v35, v38
	v_mov_b32_e32 v36, v38
	v_mov_b32_e32 v37, v38
	v_mov_b32_e32 v86, v38
	v_mov_b32_e32 v87, v38
	v_mov_b32_e32 v88, v38
	v_mov_b32_e32 v89, v38
	v_mov_b32_e32 v94, v38
	v_mov_b32_e32 v95, v38
	v_mov_b32_e32 v96, v38
	v_mov_b32_e32 v97, v38
	v_mov_b32_e32 v90, v38
	v_mov_b32_e32 v91, v38
	v_mov_b32_e32 v92, v38
	v_mov_b32_e32 v93, v38
	v_mov_b32_e32 v82, v38
	v_mov_b32_e32 v83, v38
	v_mov_b32_e32 v84, v38
	v_mov_b32_e32 v85, v38
.LBB0_413:
	s_mul_hi_u32 s27, s23, 0xaaaaaaab
	s_lshr_b32 s27, s27, 1
	s_mul_i32 s27, s27, 0x24000
	s_waitcnt lgkmcnt(0)
	v_mfma_f32_16x16x32_bf16 v[66:69], v[22:25], v[26:29], v[66:69]
	v_add_u32_e32 v222, s14, v113
	s_mul_hi_u32 s34, s19, 0xaaaaaaab
	s_lshr_b32 s34, s34, 1
	v_mfma_f32_16x16x32_bf16 v[62:65], v[18:21], v[26:29], v[62:65]
	s_mul_i32 s34, s34, 0x24000
	v_subrev_u32_e32 v182, s34, v126
	v_subrev_u32_e32 v191, s34, v127
	v_mfma_f32_16x16x32_bf16 v[58:61], v[10:13], v[26:29], v[58:61]
	v_subrev_u32_e32 v201, s34, v128
	v_mfma_f32_16x16x32_bf16 v[54:57], v[6:9], v[26:29], v[54:57]
	v_subrev_u32_e32 v26, s27, v125
	v_mfma_f32_16x16x32_bf16 v[50:53], v[22:25], v[14:17], v[50:53]
	v_mfma_f32_16x16x32_bf16 v[46:49], v[18:21], v[14:17], v[46:49]
	v_mfma_f32_16x16x32_bf16 v[42:45], v[10:13], v[14:17], v[42:45]
	v_mfma_f32_16x16x32_bf16 v[38:41], v[6:9], v[14:17], v[38:41]
	v_subrev_u32_e32 v14, s27, v129
	v_add_u32_e32 v16, v222, v26
	v_add_u32_e32 v14, v222, v14
	v_mfma_f32_16x16x32_bf16 v[34:37], v[22:25], v[30:33], v[34:37]
	v_subrev_u32_e32 v15, s34, v130
	v_mfma_f32_16x16x32_bf16 v[86:89], v[22:25], v[2:5], v[86:89]
	ds_read_b128 v[22:25], v16
	ds_read_b128 v[174:177], v16 offset:2048
	ds_read_b128 v[178:181], v16 offset:4096
	ds_read_b128 v[202:205], v16 offset:6144
	ds_read_b128 v[206:209], v14 offset:32768
	ds_read_b128 v[210:213], v14 offset:34816
	ds_read_b128 v[214:217], v14 offset:36864
	ds_read_b128 v[218:221], v14 offset:38912
	v_mfma_f32_16x16x32_bf16 v[74:77], v[18:21], v[30:33], v[74:77]
	v_mfma_f32_16x16x32_bf16 v[70:73], v[10:13], v[30:33], v[70:73]
	v_mfma_f32_16x16x32_bf16 v[78:81], v[6:9], v[30:33], v[78:81]
	v_mfma_f32_16x16x32_bf16 v[94:97], v[18:21], v[2:5], v[94:97]
	v_mfma_f32_16x16x32_bf16 v[90:93], v[10:13], v[2:5], v[90:93]
	v_mfma_f32_16x16x32_bf16 v[82:85], v[6:9], v[2:5], v[82:85]
	s_add_i32 s27, s13, 4
	s_mul_i32 s34, s27, 0xab
	s_bfe_u32 s34, s34, 0x70009
	s_mul_i32 s34, s34, 3
	s_sub_i32 s27, s27, s34
	s_and_b32 s27, s27, 0xff
	s_mul_i32 s27, s27, 0xc000
	s_waitcnt vmcnt(6)
	v_add_u32_e32 v2, v222, v15
	v_add_u32_e32 v6, v222, v201
	s_waitcnt lgkmcnt(0)
	v_mfma_f32_16x16x32_bf16 v[66:69], v[206:209], v[174:177], v[66:69]
	s_mov_b64 s[36:37], 0xe1d8180
	s_add_i32 s34, s27, s8
	s_waitcnt lgkmcnt(0)
	v_mfma_f32_16x16x32_bf16 v[62:65], v[210:213], v[174:177], v[62:65]
	s_barrier
	ds_read_b128 v[30:33], v2
	ds_read_b128 v[26:29], v2 offset:2048
	ds_read_b128 v[14:17], v2 offset:4096
	ds_read_b128 v[2:5], v2 offset:6144
	v_mfma_f32_16x16x32_bf16 v[58:61], v[214:217], v[174:177], v[58:61]
	v_add_u32_e32 v7, v222, v191
	s_mov_b32 m0, s34
	s_add_i32 s27, s27, s9
	v_mfma_f32_16x16x32_bf16 v[54:57], v[218:221], v[174:177], v[54:57]
	v_lshl_add_u64 v[174:175], v[108:109], 0, v[98:99]
	v_lshl_add_u64 v[176:177], v[174:175], 0, s[36:37]
	s_mov_b64 s[36:37], 0xe1e8180
	v_mfma_f32_16x16x32_bf16 v[34:37], v[206:209], v[22:25], v[34:37]
	s_add_i32 s23, s23, 1
	v_mfma_f32_16x16x32_bf16 v[74:77], v[210:213], v[22:25], v[74:77]
	v_mfma_f32_16x16x32_bf16 v[70:73], v[214:217], v[22:25], v[70:73]
	v_mfma_f32_16x16x32_bf16 v[78:81], v[218:221], v[22:25], v[78:81]
	ds_read_b128 v[22:25], v6
	ds_read_b128 v[18:21], v7
	v_add_u32_e32 v6, v222, v182
	ds_read_b128 v[10:13], v6
	ds_read_b128 v[6:9], v6 offset:2048
	global_load_lds_dwordx4 v[176:177], off sc1
	v_lshl_add_u64 v[176:177], v[174:175], 0, s[36:37]
	s_add_i32 m0, s34, 0x400
	s_mov_b64 s[36:37], 0xe1f8180
	global_load_lds_dwordx4 v[176:177], off sc1
	v_lshl_add_u64 v[176:177], v[174:175], 0, s[36:37]
	s_add_i32 m0, s34, 0x800
	s_mov_b64 s[36:37], 0xe208180
	global_load_lds_dwordx4 v[176:177], off sc1
	v_lshl_add_u64 v[174:175], v[174:175], 0, s[36:37]
	s_add_i32 m0, s34, 0xc00
	s_mov_b64 s[36:37], 0x4300180
	global_load_lds_dwordx4 v[174:175], off sc1
	v_lshl_add_u64 v[174:175], v[110:111], 0, v[98:99]
	v_lshl_add_u64 v[176:177], v[174:175], 0, s[36:37]
	s_add_i32 m0, s27, 0x8000
	s_mov_b64 s[36:37], 0x4310180
	global_load_lds_dwordx4 v[176:177], off sc1
	v_lshl_add_u64 v[174:175], v[174:175], 0, s[36:37]
	s_add_i32 m0, s27, 0x8400
	v_mfma_f32_16x16x32_bf16 v[50:53], v[206:209], v[178:181], v[50:53]
	global_load_lds_dwordx4 v[174:175], off sc1
	v_mfma_f32_16x16x32_bf16 v[46:49], v[210:213], v[178:181], v[46:49]
	v_mfma_f32_16x16x32_bf16 v[42:45], v[214:217], v[178:181], v[42:45]
	v_mfma_f32_16x16x32_bf16 v[38:41], v[218:221], v[178:181], v[38:41]
	v_mfma_f32_16x16x32_bf16 v[86:89], v[206:209], v[202:205], v[86:89]
	v_mfma_f32_16x16x32_bf16 v[94:97], v[210:213], v[202:205], v[94:97]
	v_mfma_f32_16x16x32_bf16 v[90:93], v[214:217], v[202:205], v[90:93]
	v_mfma_f32_16x16x32_bf16 v[82:85], v[218:221], v[202:205], v[82:85]
	s_add_i32 s13, s13, 1
	s_add_i32 s14, s14, 0xc000
	s_add_i32 s19, s19, 1
	s_mov_b32 s36, 0xffffe080
	s_mov_b32 s37, -1
	s_cmp_eq_u32 s23, s55
	s_cselect_b64 s[36:37], s[36:37], s[2:3]
	v_lshl_add_u64 v[108:109], v[108:109], 0, s[36:37]
	v_lshl_add_u64 v[110:111], v[110:111], 0, s[36:37]
	s_cmp_eq_u32 s14, 0x2dc000
	s_cbranch_scc0 .LBB0_413
	s_waitcnt lgkmcnt(0)
	v_mfma_f32_16x16x32_bf16 v[34:37], v[22:25], v[30:33], v[34:37]
	v_mfma_f32_16x16x32_bf16 v[74:77], v[18:21], v[30:33], v[74:77]
	v_mfma_f32_16x16x32_bf16 v[70:73], v[10:13], v[30:33], v[70:73]
	v_mfma_f32_16x16x32_bf16 v[30:33], v[6:9], v[30:33], v[78:81]
	v_mfma_f32_16x16x32_bf16 v[66:69], v[22:25], v[26:29], v[66:69]
	v_mfma_f32_16x16x32_bf16 v[62:65], v[18:21], v[26:29], v[62:65]
	v_mfma_f32_16x16x32_bf16 v[58:61], v[10:13], v[26:29], v[58:61]
	v_mfma_f32_16x16x32_bf16 v[26:29], v[6:9], v[26:29], v[54:57]
	v_mfma_f32_16x16x32_bf16 v[50:53], v[22:25], v[14:17], v[50:53]
	v_mfma_f32_16x16x32_bf16 v[46:49], v[18:21], v[14:17], v[46:49]
	v_mfma_f32_16x16x32_bf16 v[42:45], v[10:13], v[14:17], v[42:45]
	v_mfma_f32_16x16x32_bf16 v[14:17], v[6:9], v[14:17], v[38:41]
	v_mfma_f32_16x16x32_bf16 v[22:25], v[22:25], v[2:5], v[86:89]
	s_nop 1
	ds_read_b128 v[38:41], v131
	ds_read_b128 v[54:57], v132 offset:2048
	ds_read_b128 v[78:81], v132 offset:4096
	ds_read_b128 v[86:89], v132 offset:6144
	v_mfma_f32_16x16x32_bf16 v[18:21], v[18:21], v[2:5], v[94:97]
	v_mfma_f32_16x16x32_bf16 v[10:13], v[10:13], v[2:5], v[90:93]
	s_nop 2
	ds_read_b128 v[90:93], v133 offset:32768
	ds_read_b128 v[94:97], v134 offset:34816
	ds_read_b128 v[108:111], v134 offset:36864
	ds_read_b128 v[174:177], v134 offset:38912
	v_mfma_f32_16x16x32_bf16 v[2:5], v[6:9], v[2:5], v[82:85]
	s_waitcnt lgkmcnt(0)
	v_mfma_f32_16x16x32_bf16 v[6:9], v[90:93], v[38:41], v[34:37]
	s_waitcnt vmcnt(6)
	s_waitcnt lgkmcnt(0)
	s_barrier
	v_mfma_f32_16x16x32_bf16 v[34:37], v[94:97], v[38:41], v[74:77]
	v_mfma_f32_16x16x32_bf16 v[70:73], v[108:111], v[38:41], v[70:73]
	v_mfma_f32_16x16x32_bf16 v[30:33], v[174:177], v[38:41], v[30:33]
	v_mfma_f32_16x16x32_bf16 v[38:41], v[90:93], v[54:57], v[66:69]
	v_mfma_f32_16x16x32_bf16 v[62:65], v[94:97], v[54:57], v[62:65]
	v_mfma_f32_16x16x32_bf16 v[58:61], v[108:111], v[54:57], v[58:61]
	v_mfma_f32_16x16x32_bf16 v[26:29], v[174:177], v[54:57], v[26:29]
	v_add_u32_e32 v54, v124, v115
	ds_read_b128 v[54:57], v54
	ds_read_b128 v[66:69], v135 offset:2048
	v_mfma_f32_16x16x32_bf16 v[50:53], v[90:93], v[78:81], v[50:53]
	v_mfma_f32_16x16x32_bf16 v[46:49], v[94:97], v[78:81], v[46:49]
	v_mfma_f32_16x16x32_bf16 v[42:45], v[108:111], v[78:81], v[42:45]
	v_mfma_f32_16x16x32_bf16 v[22:25], v[90:93], v[86:89], v[22:25]
	v_add_u32_e32 v90, 0x20800, v164
	v_mfma_f32_16x16x32_bf16 v[18:21], v[94:97], v[86:89], v[18:21]
	v_add_u32_e32 v94, 0x21000, v164
	v_mfma_f32_16x16x32_bf16 v[10:13], v[108:111], v[86:89], v[10:13]
	v_add_u32_e32 v108, 0x21800, v164
	v_mfma_f32_16x16x32_bf16 v[14:17], v[174:177], v[78:81], v[14:17]
	ds_read_b128 v[74:77], v135 offset:4096
	ds_read_b128 v[78:81], v135 offset:6144
	ds_read_b128 v[82:85], v163
	ds_read_b128 v[90:93], v90
	ds_read_b128 v[94:97], v94
	ds_read_b128 v[108:111], v108
	v_mfma_f32_16x16x32_bf16 v[2:5], v[174:177], v[86:89], v[2:5]
	s_waitcnt lgkmcnt(0)
	v_mfma_f32_16x16x32_bf16 v[6:9], v[82:85], v[54:57], v[6:9]
	v_mfma_f32_16x16x32_bf16 v[34:37], v[90:93], v[54:57], v[34:37]
	v_mfma_f32_16x16x32_bf16 v[70:73], v[94:97], v[54:57], v[70:73]
	v_mfma_f32_16x16x32_bf16 v[30:33], v[108:111], v[54:57], v[30:33]
	v_mfma_f32_16x16x32_bf16 v[54:57], v[90:93], v[66:69], v[62:65]
	s_nop 2
	v_add_u32_e32 v62, v124, v119
	v_mfma_f32_16x16x32_bf16 v[38:41], v[82:85], v[66:69], v[38:41]
	v_mfma_f32_16x16x32_bf16 v[58:61], v[94:97], v[66:69], v[58:61]
	v_mfma_f32_16x16x32_bf16 v[26:29], v[108:111], v[66:69], v[26:29]
	v_mfma_f32_16x16x32_bf16 v[50:53], v[82:85], v[74:77], v[50:53]
	v_mfma_f32_16x16x32_bf16 v[46:49], v[90:93], v[74:77], v[46:49]
	v_mfma_f32_16x16x32_bf16 v[42:45], v[94:97], v[74:77], v[42:45]
	v_mfma_f32_16x16x32_bf16 v[14:17], v[108:111], v[74:77], v[14:17]
	v_mfma_f32_16x16x32_bf16 v[22:25], v[82:85], v[78:81], v[22:25]
	ds_read_b128 v[62:65], v62
	ds_read_b128 v[66:69], v165
	ds_read_b128 v[74:77], v166
	ds_read_b128 v[82:85], v167
	v_mfma_f32_16x16x32_bf16 v[18:21], v[90:93], v[78:81], v[18:21]
	v_mfma_f32_16x16x32_bf16 v[10:13], v[94:97], v[78:81], v[10:13]
	ds_read_b128 v[86:89], v168
	ds_read_b128 v[90:93], v169
	ds_read_b128 v[94:97], v170
	ds_read_b128 v[174:177], v171
	v_mfma_f32_16x16x32_bf16 v[2:5], v[108:111], v[78:81], v[2:5]
	s_waitcnt vmcnt(0)
	s_waitcnt lgkmcnt(0)
	v_mfma_f32_16x16x32_bf16 v[6:9], v[86:89], v[62:65], v[6:9]
	s_waitcnt lgkmcnt(0)
	s_barrier
	v_mfma_f32_16x16x32_bf16 v[34:37], v[90:93], v[62:65], v[34:37]
	v_mfma_f32_16x16x32_bf16 v[70:73], v[94:97], v[62:65], v[70:73]
	v_mfma_f32_16x16x32_bf16 v[30:33], v[174:177], v[62:65], v[30:33]
	v_mfma_f32_16x16x32_bf16 v[38:41], v[86:89], v[66:69], v[38:41]
	v_mfma_f32_16x16x32_bf16 v[54:57], v[90:93], v[66:69], v[54:57]
	v_mfma_f32_16x16x32_bf16 v[58:61], v[94:97], v[66:69], v[58:61]
	v_mfma_f32_16x16x32_bf16 v[26:29], v[174:177], v[66:69], v[26:29]
	v_mfma_f32_16x16x32_bf16 v[50:53], v[86:89], v[74:77], v[50:53]
	v_mfma_f32_16x16x32_bf16 v[46:49], v[90:93], v[74:77], v[46:49]
	v_mfma_f32_16x16x32_bf16 v[42:45], v[94:97], v[74:77], v[42:45]
	v_mfma_f32_16x16x32_bf16 v[14:17], v[174:177], v[74:77], v[14:17]
	ds_read_b128 v[62:65], v164 offset:38912
	ds_read_b128 v[66:69], v164 offset:36864
	ds_read_b128 v[74:77], v164 offset:34816
	ds_read_b128 v[78:81], v161 offset:32768
	v_mfma_f32_16x16x32_bf16 v[22:25], v[86:89], v[82:85], v[22:25]
	v_mfma_f32_16x16x32_bf16 v[18:21], v[90:93], v[82:85], v[18:21]
	v_mfma_f32_16x16x32_bf16 v[10:13], v[94:97], v[82:85], v[10:13]
	ds_read_b128 v[86:89], v173 offset:6144
	ds_read_b128 v[90:93], v173 offset:4096
	ds_read_b128 v[94:97], v173 offset:2048
	ds_read_b128 v[108:111], v172
	v_mfma_f32_16x16x32_bf16 v[2:5], v[174:177], v[82:85], v[2:5]
	s_waitcnt lgkmcnt(0)
	v_mfma_f32_16x16x32_bf16 v[38:41], v[78:81], v[94:97], v[38:41]
	v_add_u32_e32 v82, v114, v119
	v_add_u32_e32 v172, v118, v119
	v_mfma_f32_16x16x32_bf16 v[54:57], v[74:77], v[94:97], v[54:57]
	v_mfma_f32_16x16x32_bf16 v[58:61], v[66:69], v[94:97], v[58:61]
	v_mfma_f32_16x16x32_bf16 v[26:29], v[62:65], v[94:97], v[26:29]
	v_add_u32_e32 v94, v117, v119
	v_mfma_f32_16x16x32_bf16 v[50:53], v[78:81], v[90:93], v[50:53]
	v_mfma_f32_16x16x32_bf16 v[46:49], v[74:77], v[90:93], v[46:49]
	v_mfma_f32_16x16x32_bf16 v[42:45], v[66:69], v[90:93], v[42:45]
	v_mfma_f32_16x16x32_bf16 v[14:17], v[62:65], v[90:93], v[14:17]
	v_add_u32_e32 v90, v116, v119
	v_mfma_f32_16x16x32_bf16 v[6:9], v[78:81], v[108:111], v[6:9]
	v_mfma_f32_16x16x32_bf16 v[34:37], v[74:77], v[108:111], v[34:37]
	v_mfma_f32_16x16x32_bf16 v[70:73], v[66:69], v[108:111], v[70:73]
	v_mfma_f32_16x16x32_bf16 v[30:33], v[62:65], v[108:111], v[30:33]
	v_mfma_f32_16x16x32_bf16 v[78:81], v[78:81], v[86:89], v[22:25]
	s_nop 2
	ds_read_b128 v[22:25], v82
	ds_read_b128 v[82:85], v90 offset:2048
	v_mfma_f32_16x16x32_bf16 v[74:77], v[74:77], v[86:89], v[18:21]
	s_nop 2
	ds_read_b128 v[18:21], v90 offset:4096
	ds_read_b128 v[90:93], v90 offset:6144
	v_mfma_f32_16x16x32_bf16 v[66:69], v[66:69], v[86:89], v[10:13]
	s_nop 2
	ds_read_b128 v[10:13], v94 offset:32768
	ds_read_b128 v[94:97], v172 offset:34816
	ds_read_b128 v[108:111], v172 offset:36864
	ds_read_b128 v[172:175], v172 offset:38912
	v_mfma_f32_16x16x32_bf16 v[2:5], v[62:65], v[86:89], v[2:5]
	s_waitcnt vmcnt(0)
	s_waitcnt lgkmcnt(0)
	v_mfma_f32_16x16x32_bf16 v[2:5], v[172:175], v[90:93], v[2:5]
	s_waitcnt lgkmcnt(0)
	s_barrier
	v_mfma_f32_16x16x32_bf16 v[62:65], v[10:13], v[22:25], v[6:9]
	v_mfma_f32_16x16x32_bf16 v[86:89], v[94:97], v[22:25], v[34:37]
	v_mfma_f32_16x16x32_bf16 v[70:73], v[108:111], v[22:25], v[70:73]
	v_mfma_f32_16x16x32_bf16 v[176:179], v[172:175], v[22:25], v[30:33]
	v_mfma_f32_16x16x32_bf16 v[202:205], v[10:13], v[82:85], v[38:41]
	v_mfma_f32_16x16x32_bf16 v[54:57], v[94:97], v[82:85], v[54:57]
	v_mfma_f32_16x16x32_bf16 v[58:61], v[108:111], v[82:85], v[58:61]
	v_mfma_f32_16x16x32_bf16 v[34:37], v[172:175], v[82:85], v[26:29]
	v_mfma_f32_16x16x32_bf16 v[30:33], v[10:13], v[18:21], v[50:53]
	v_mfma_f32_16x16x32_bf16 v[26:29], v[94:97], v[18:21], v[46:49]
	v_mfma_f32_16x16x32_bf16 v[22:25], v[108:111], v[18:21], v[42:45]
	v_mfma_f32_16x16x32_bf16 v[18:21], v[172:175], v[18:21], v[14:17]
	v_mfma_f32_16x16x32_bf16 v[14:17], v[10:13], v[90:93], v[78:81]
	v_mfma_f32_16x16x32_bf16 v[10:13], v[94:97], v[90:93], v[74:77]
	v_mfma_f32_16x16x32_bf16 v[6:9], v[108:111], v[90:93], v[66:69]
	s_mul_hi_i32 s54, s70, 0x2aaaaaab
	s_lshr_b32 s55, s54, 31
	s_ashr_i32 s54, s54, 2
	s_add_i32 s13, s54, s55
	s_mul_i32 s54, s13, 24
	s_sub_i32 s14, s70, s54
	v_readfirstlane_b32 s54, v137
	s_lshr_b32 s54, s54, 6
	s_and_b32 s19, s54, 1
	s_lshr_b32 s54, s54, 1
	s_lshl_b32 s54, s54, 6
	s_lshl_b32 s50, s14, 8
	s_add_i32 s50, s50, s54
	s_lshl_b32 s51, s13, 7
	s_lshl_b32 s54, s19, 6
	s_add_i32 s51, s51, s54
	s_add_i32 s54, s50, 0xfffff000
	s_ashr_i32 s54, s54, 10
	s_add_i32 s54, s54, 1
	s_cmpk_lt_i32 s50, 0x1000
	s_cselect_b32 s52, 0, s54
	v_readlane_b32 s53, v255, 40
	v_and_b32_e32 v250, 63, v137
	v_and_b32_e32 v251, 15, v250
	v_lshrrev_b32_e32 v252, 4, v250
	s_mul_i32 s54, s53, 3
	s_add_i32 s54, s54, s52
	s_mul_i32 s54, s54, 0x6000
	s_add_u32 s22, s94, 0x6300000
	s_addc_u32 s23, s95, 0
	s_add_u32 s22, s22, s54
	s_addc_u32 s23, s23, 0
	s_add_u32 s26, s94, 0x6348000
	s_addc_u32 s27, s95, 0
	v_add_u32_e32 v242, s50, v251
	v_lshlrev_b32_e32 v242, 12, v242
	s_lshl_b32 s54, s51, 2
	v_lshl_add_u32 v242, v252, 4, v242
	v_add_u32_e32 v242, s54, v242
	s_add_i32 s55, s51, 5120
	s_lshl_b32 s55, s55, 2
	v_lshl_add_u32 v246, v252, 4, s55
	v_add_u32_e32 v243, 0x10000, v242
	v_add_u32_e32 v244, 0x20000, v242
	v_add_u32_e32 v245, 0x30000, v242
	global_load_dwordx4 v[226:229], v246, s[22:23] sc1
	global_load_dwordx4 v[230:233], v246, s[22:23] offset:64 sc1
	global_load_dwordx4 v[234:237], v246, s[22:23] offset:128 sc1
	global_load_dwordx4 v[238:241], v246, s[22:23] offset:192 sc1
	global_load_dwordx4 v[38:41], v242, s[26:27] sc1
	global_load_dwordx4 v[42:45], v242, s[26:27] offset:64 sc1
	global_load_dwordx4 v[46:49], v242, s[26:27] offset:128 sc1
	global_load_dwordx4 v[50:53], v242, s[26:27] offset:192 sc1
	global_load_dwordx4 v[66:69], v243, s[26:27] sc1
	global_load_dwordx4 v[74:77], v243, s[26:27] offset:64 sc1
	global_load_dwordx4 v[78:81], v243, s[26:27] offset:128 sc1
	global_load_dwordx4 v[82:85], v243, s[26:27] offset:192 sc1
	global_load_dwordx4 v[90:93], v244, s[26:27] sc1
	global_load_dwordx4 v[94:97], v244, s[26:27] offset:64 sc1
	global_load_dwordx4 v[108:111], v244, s[26:27] offset:128 sc1
	global_load_dwordx4 v[172:175], v244, s[26:27] offset:192 sc1
	global_load_dwordx4 v[206:209], v245, s[26:27] sc1
	global_load_dwordx4 v[210:213], v245, s[26:27] offset:64 sc1
	global_load_dwordx4 v[214:217], v245, s[26:27] offset:128 sc1
	global_load_dwordx4 v[218:221], v245, s[26:27] offset:192 sc1
	v_mov_b32_e32 v248, 0x3fd744fd
	v_mov_b32_e32 v249, 0x3fd744fd
	s_waitcnt vmcnt(12)
	v_pk_mul_f32 v[38:39], v[38:39], v[248:249]
	v_pk_mul_f32 v[40:41], v[40:41], v[248:249]
	v_pk_fma_f32 v[62:63], v[62:63], v[226:227], v[38:39]
	v_pk_fma_f32 v[64:65], v[64:65], v[228:229], v[40:41]
	v_pk_mul_f32 v[42:43], v[42:43], v[248:249]
	v_pk_mul_f32 v[44:45], v[44:45], v[248:249]
	v_pk_fma_f32 v[86:87], v[86:87], v[230:231], v[42:43]
	v_pk_fma_f32 v[88:89], v[88:89], v[232:233], v[44:45]
	v_pk_mul_f32 v[46:47], v[46:47], v[248:249]
	v_pk_mul_f32 v[48:49], v[48:49], v[248:249]
	v_pk_fma_f32 v[70:71], v[70:71], v[234:235], v[46:47]
	v_pk_fma_f32 v[72:73], v[72:73], v[236:237], v[48:49]
	v_pk_mul_f32 v[50:51], v[50:51], v[248:249]
	v_pk_mul_f32 v[52:53], v[52:53], v[248:249]
	v_pk_fma_f32 v[176:177], v[176:177], v[238:239], v[50:51]
	v_pk_fma_f32 v[178:179], v[178:179], v[240:241], v[52:53]
	s_waitcnt vmcnt(8)
	v_pk_mul_f32 v[66:67], v[66:67], v[248:249]
	v_pk_mul_f32 v[68:69], v[68:69], v[248:249]
	v_pk_fma_f32 v[202:203], v[202:203], v[226:227], v[66:67]
	v_pk_fma_f32 v[204:205], v[204:205], v[228:229], v[68:69]
	v_pk_mul_f32 v[74:75], v[74:75], v[248:249]
	v_pk_mul_f32 v[76:77], v[76:77], v[248:249]
	v_pk_fma_f32 v[54:55], v[54:55], v[230:231], v[74:75]
	v_pk_fma_f32 v[56:57], v[56:57], v[232:233], v[76:77]
	v_pk_mul_f32 v[78:79], v[78:79], v[248:249]
	v_pk_mul_f32 v[80:81], v[80:81], v[248:249]
	v_pk_fma_f32 v[58:59], v[58:59], v[234:235], v[78:79]
	v_pk_fma_f32 v[60:61], v[60:61], v[236:237], v[80:81]
	v_pk_mul_f32 v[82:83], v[82:83], v[248:249]
	v_pk_mul_f32 v[84:85], v[84:85], v[248:249]
	v_pk_fma_f32 v[34:35], v[34:35], v[238:239], v[82:83]
	v_pk_fma_f32 v[36:37], v[36:37], v[240:241], v[84:85]
	s_waitcnt vmcnt(4)
	v_pk_mul_f32 v[90:91], v[90:91], v[248:249]
	v_pk_mul_f32 v[92:93], v[92:93], v[248:249]
	v_pk_fma_f32 v[30:31], v[30:31], v[226:227], v[90:91]
	v_pk_fma_f32 v[32:33], v[32:33], v[228:229], v[92:93]
	v_pk_mul_f32 v[94:95], v[94:95], v[248:249]
	v_pk_mul_f32 v[96:97], v[96:97], v[248:249]
	v_pk_fma_f32 v[26:27], v[26:27], v[230:231], v[94:95]
	v_pk_fma_f32 v[28:29], v[28:29], v[232:233], v[96:97]
	v_pk_mul_f32 v[108:109], v[108:109], v[248:249]
	v_pk_mul_f32 v[110:111], v[110:111], v[248:249]
	v_pk_fma_f32 v[22:23], v[22:23], v[234:235], v[108:109]
	v_pk_fma_f32 v[24:25], v[24:25], v[236:237], v[110:111]
	v_pk_mul_f32 v[172:173], v[172:173], v[248:249]
	v_pk_mul_f32 v[174:175], v[174:175], v[248:249]
	v_pk_fma_f32 v[18:19], v[18:19], v[238:239], v[172:173]
	v_pk_fma_f32 v[20:21], v[20:21], v[240:241], v[174:175]
	s_waitcnt vmcnt(0)
	v_pk_mul_f32 v[206:207], v[206:207], v[248:249]
	v_pk_mul_f32 v[208:209], v[208:209], v[248:249]
	v_pk_fma_f32 v[14:15], v[14:15], v[226:227], v[206:207]
	v_pk_fma_f32 v[16:17], v[16:17], v[228:229], v[208:209]
	v_pk_mul_f32 v[210:211], v[210:211], v[248:249]
	v_pk_mul_f32 v[212:213], v[212:213], v[248:249]
	v_pk_fma_f32 v[10:11], v[10:11], v[230:231], v[210:211]
	v_pk_fma_f32 v[12:13], v[12:13], v[232:233], v[212:213]
	v_pk_mul_f32 v[214:215], v[214:215], v[248:249]
	v_pk_mul_f32 v[216:217], v[216:217], v[248:249]
	v_pk_fma_f32 v[6:7], v[6:7], v[234:235], v[214:215]
	v_pk_fma_f32 v[8:9], v[8:9], v[236:237], v[216:217]
	v_pk_mul_f32 v[218:219], v[218:219], v[248:249]
	v_pk_mul_f32 v[220:221], v[220:221], v[248:249]
	v_pk_fma_f32 v[2:3], v[2:3], v[238:239], v[218:219]
	v_pk_fma_f32 v[4:5], v[4:5], v[240:241], v[220:221]
	v_pk_mul_f32 v[208:209], v[62:63], v[62:63]
	v_pk_add_f32 v[206:207], v[62:63], v[64:65]
	v_pk_fma_f32 v[208:209], v[64:65], v[64:65], v[208:209]
	v_pk_add_f32 v[206:207], v[206:207], v[86:87]
	v_pk_fma_f32 v[208:209], v[86:87], v[86:87], v[208:209]
	v_pk_add_f32 v[206:207], v[206:207], v[88:89]
	v_pk_fma_f32 v[208:209], v[88:89], v[88:89], v[208:209]
	v_pk_add_f32 v[206:207], v[206:207], v[70:71]
	v_pk_fma_f32 v[208:209], v[70:71], v[70:71], v[208:209]
	v_pk_add_f32 v[206:207], v[206:207], v[72:73]
	v_pk_fma_f32 v[208:209], v[72:73], v[72:73], v[208:209]
	v_pk_add_f32 v[206:207], v[206:207], v[176:177]
	v_pk_fma_f32 v[208:209], v[176:177], v[176:177], v[208:209]
	v_pk_add_f32 v[206:207], v[206:207], v[178:179]
	v_pk_fma_f32 v[208:209], v[178:179], v[178:179], v[208:209]
	v_add_f32_e32 v206, v206, v207
	v_add_f32_e32 v208, v208, v209
	v_pk_mul_f32 v[212:213], v[202:203], v[202:203]
	v_pk_add_f32 v[210:211], v[202:203], v[204:205]
	v_pk_fma_f32 v[212:213], v[204:205], v[204:205], v[212:213]
	v_pk_add_f32 v[210:211], v[210:211], v[54:55]
	v_pk_fma_f32 v[212:213], v[54:55], v[54:55], v[212:213]
	v_pk_add_f32 v[210:211], v[210:211], v[56:57]
	v_pk_fma_f32 v[212:213], v[56:57], v[56:57], v[212:213]
	v_pk_add_f32 v[210:211], v[210:211], v[58:59]
	v_pk_fma_f32 v[212:213], v[58:59], v[58:59], v[212:213]
	v_pk_add_f32 v[210:211], v[210:211], v[60:61]
	v_pk_fma_f32 v[212:213], v[60:61], v[60:61], v[212:213]
	v_pk_add_f32 v[210:211], v[210:211], v[34:35]
	v_pk_fma_f32 v[212:213], v[34:35], v[34:35], v[212:213]
	v_pk_add_f32 v[210:211], v[210:211], v[36:37]
	v_pk_fma_f32 v[212:213], v[36:37], v[36:37], v[212:213]
	v_add_f32_e32 v210, v210, v211
	v_add_f32_e32 v212, v212, v213
	v_pk_mul_f32 v[216:217], v[30:31], v[30:31]
	v_pk_add_f32 v[214:215], v[30:31], v[32:33]
	v_pk_fma_f32 v[216:217], v[32:33], v[32:33], v[216:217]
	v_pk_add_f32 v[214:215], v[214:215], v[26:27]
	v_pk_fma_f32 v[216:217], v[26:27], v[26:27], v[216:217]
	v_pk_add_f32 v[214:215], v[214:215], v[28:29]
	v_pk_fma_f32 v[216:217], v[28:29], v[28:29], v[216:217]
	v_pk_add_f32 v[214:215], v[214:215], v[22:23]
	v_pk_fma_f32 v[216:217], v[22:23], v[22:23], v[216:217]
	v_pk_add_f32 v[214:215], v[214:215], v[24:25]
	v_pk_fma_f32 v[216:217], v[24:25], v[24:25], v[216:217]
	v_pk_add_f32 v[214:215], v[214:215], v[18:19]
	v_pk_fma_f32 v[216:217], v[18:19], v[18:19], v[216:217]
	v_pk_add_f32 v[214:215], v[214:215], v[20:21]
	v_pk_fma_f32 v[216:217], v[20:21], v[20:21], v[216:217]
	v_add_f32_e32 v214, v214, v215
	v_add_f32_e32 v216, v216, v217
	v_pk_mul_f32 v[220:221], v[14:15], v[14:15]
	v_pk_add_f32 v[218:219], v[14:15], v[16:17]
	v_pk_fma_f32 v[220:221], v[16:17], v[16:17], v[220:221]
	v_pk_add_f32 v[218:219], v[218:219], v[10:11]
	v_pk_fma_f32 v[220:221], v[10:11], v[10:11], v[220:221]
	v_pk_add_f32 v[218:219], v[218:219], v[12:13]
	v_pk_fma_f32 v[220:221], v[12:13], v[12:13], v[220:221]
	v_pk_add_f32 v[218:219], v[218:219], v[6:7]
	v_pk_fma_f32 v[220:221], v[6:7], v[6:7], v[220:221]
	v_pk_add_f32 v[218:219], v[218:219], v[8:9]
	v_pk_fma_f32 v[220:221], v[8:9], v[8:9], v[220:221]
	v_pk_add_f32 v[218:219], v[218:219], v[2:3]
	v_pk_fma_f32 v[220:221], v[2:3], v[2:3], v[220:221]
	v_pk_add_f32 v[218:219], v[218:219], v[4:5]
	v_pk_fma_f32 v[220:221], v[4:5], v[4:5], v[220:221]
	v_add_f32_e32 v218, v218, v219
	v_add_f32_e32 v220, v220, v221
	s_nop 1
	v_permlane16_swap_b32_e32 v206, v210
	v_permlane16_swap_b32_e32 v214, v218
	v_permlane16_swap_b32_e32 v208, v212
	v_permlane16_swap_b32_e32 v216, v220
	v_add_f32_e32 v206, v206, v210
	v_add_f32_e32 v214, v214, v218
	v_add_f32_e32 v208, v208, v212
	v_add_f32_e32 v216, v216, v220
	s_nop 1
	v_permlane32_swap_b32_e32 v206, v214
	v_permlane32_swap_b32_e32 v208, v216
	v_add_f32_e32 v248, v206, v214
	v_add_f32_e32 v249, v208, v216
	s_lshl_b32 s54, s53, 1
	s_add_i32 s54, s54, 0x2c7e91a1
	v_mov_b32_e32 v218, v248
	v_mov_b32_e32 v219, s54
	v_mov_b32_e32 v220, v249
	v_mov_b32_e32 v221, s54
	v_mov_b32_e32 v249, s54
	s_add_u32 s34, s94, 0xc9d8000
	s_addc_u32 s35, s95, 0
	v_add_u32_e32 v247, s50, v250
	v_lshlrev_b32_e32 v247, 4, v247
	s_lshl_b32 s55, s13, 1
	s_add_i32 s55, s55, s19
	s_mul_i32 s55, s55, 0x18000
	v_add_u32_e32 v246, s55, v247
	global_store_dwordx4 v246, v[218:221], s[34:35] sc1
	v_readlane_b32 s36, v253, 15
	v_readlane_b32 s37, v253, 16
	v_readlane_b32 s48, v253, 17
	v_readlane_b32 s49, v253, 18
	s_lshl_b32 s54, s53, 10
	s_add_i32 s54, s54, s51
	s_lshl_b32 s54, s54, 2
	v_lshl_add_u32 v222, v252, 4, s54
	s_nop 3
	global_load_dwordx4 v[66:69], v222, s[36:37] sc1
	global_load_dwordx4 v[74:77], v222, s[36:37] offset:64 sc1
	global_load_dwordx4 v[78:81], v222, s[36:37] offset:128 sc1
	global_load_dwordx4 v[82:85], v222, s[36:37] offset:192 sc1
	global_load_dwordx4 v[90:93], v222, s[48:49] sc1
	global_load_dwordx4 v[94:97], v222, s[48:49] offset:64 sc1
	global_load_dwordx4 v[108:111], v222, s[48:49] offset:128 sc1
	global_load_dwordx4 v[172:175], v222, s[48:49] offset:192 sc1
	s_add_u32 s22, s22, 0x12000
	s_addc_u32 s23, s23, 0
	s_add_i32 s54, s51, 0
	s_lshl_b32 s54, s54, 2
	v_lshl_add_u32 v222, v252, 4, s54
	v_add_u32_e32 v246, 0x1000, v222
	s_cmp_eq_u32 s53, 3
	s_cbranch_scc1 .Lln2_nosh
	global_load_dwordx4 v[38:41], v222, s[22:23] sc1
	global_load_dwordx4 v[42:45], v222, s[22:23] offset:64 sc1
	global_load_dwordx4 v[46:49], v222, s[22:23] offset:128 sc1
	global_load_dwordx4 v[50:53], v222, s[22:23] offset:192 sc1

.Lln2_pok1:
	v_add_f32_e32 v250, v250, v226
	v_add_f32_e32 v252, v252, v228
	v_add_f32_e32 v250, v250, v230
	v_add_f32_e32 v252, v252, v232
	v_add_f32_e32 v250, v250, v234
	v_add_f32_e32 v252, v252, v236
	v_add_f32_e32 v250, v250, v238
	v_add_f32_e32 v252, v252, v240
	v_add_f32_e32 v250, v250, v206
	v_add_f32_e32 v252, v252, v208
	v_add_f32_e32 v250, v250, v210
	v_add_f32_e32 v252, v252, v212
	v_add_f32_e32 v250, v250, v214
	v_add_f32_e32 v252, v252, v216
	v_add_f32_e32 v250, v250, v218
	v_add_f32_e32 v252, v252, v220
	s_cmp_eq_u32 s53, 3
	s_cbranch_scc1 .Lln2_nomod
	global_load_dwordx4 v[226:229], v246, s[22:23] sc1
	global_load_dwordx4 v[230:233], v246, s[22:23] offset:64 sc1
	global_load_dwordx4 v[234:237], v246, s[22:23] offset:128 sc1
	global_load_dwordx4 v[238:241], v246, s[22:23] offset:192 sc1
